# tail-round split: GU1/GU2 layer-1 last round shares each 256x256 tile between two workgroups (128 rows each, second super-phase MFMAs and second epilogue half skipped)
# speedup vs baseline: 1.0023x; 1.0023x over previous
; #define PG8_STAGE(bufoff, gbase, voff) do { _Pragma("unroll") for (int _i = 0; _i < 2; ++_i) \
;         __builtin_amdgcn_global_load_lds((const unsigned*)((const char*)(gbase) + (voff)[_i]), (PG8_LAS unsigned*)(lds + (bufoff) + ldsw + _i * 8192), 16, 0, 0); } while (0)
; template <class Epi, class Sched, bool ALIGN_EPI = false, bool SP2 = false, bool F16 = false, bool TOKPERM = false>
; __device__ __forceinline__ void gemm_phase(PG8_LAS unsigned char* lds, const Gemm g, const Sched& S, const Epi& E, int wv) {
;     ...
;     const int tid = tid_, wid = __builtin_amdgcn_readfirstlane(tid >> 6), lane = tid & 63, wr = wid >> 2, wc = wid & 3, fr = lane & 15, fq = lane >> 4;
;     const int K = g.K, nt = K / BK;
;     unsigned voffA[2], voffB[2];
; #pragma unroll
;     for (int i = 0; i < 2; ++i) { int R, C; stage_rc(tid * 16 + i * 8192, R, C); const int Rb = Epi::PERM ? ((R & ~31) + perm32(R & 31)) : R;
;         const int Ra = TOKPERM ? ((R & ~63) + 4 * (R & 15) + ((R >> 4) & 3)) : R;
;         voffA[i] = (unsigned)(Ra * K + C) * 2u; voffB[i] = (unsigned)(Rb * K + C) * 2u; }
;     const size_t kstep = (size_t)(BK * 2);
;     const size_t hstep = (size_t)HALF * K * 2;
;     const size_t tstep = 2 * hstep;
;     const unsigned ldsw = (unsigned)wid * 1024u;
;     const int aoff = lds_byte(wr * 64 + fr, fq * 8), boff = lds_byte(wc * 32 + fr, fq * 8);
;     ...
;     Unit cur, nxt; int ui = 0;
;     if (!S.next(0, cur)) return;
;     f32x4 acc[2][2][4][2];
; #pragma unroll
;     for (int a = 0; a < 2; ++a)
; #pragma unroll
;         for (int b = 0; b < 2; ++b)
; #pragma unroll
;             for (int m = 0; m < 4; ++m)
; #pragma unroll
;                 for (int n = 0; n < 2; ++n) acc[a][b][m][n] = (f32x4){0.f, 0.f, 0.f, 0.f};
;     bf16x8 At[4][2], B0[2][2], B1[2][2];
;     const char* cA = (const char*)g.A + (size_t)cur.pm * tstep; const char* cB = (const char*)g.Bt + (size_t)cur.pn * tstep;
;     S.a_ready(cur);
;     if constexpr (SP2) {
;         PG8_STAGE(PG8_SB(0, 0), cB, voffB); PG8_STAGE(PG8_SB(0, 1), cB + hstep, voffB); PG8_STAGE(PG8_SA(0, 0), cA, voffA); PG8_STAGE(PG8_SA(0, 1), cA + hstep, voffA);
;         if (wr == 1) PG8_BAR;
;         PG8_WAIT_V(2); PG8_BAR;
;         PG8_STAGE(PG8_SB(1, 0), cB + kstep, voffB); PG8_STAGE(PG8_SA(1, 0), cA + kstep, voffA); PG8_STAGE(PG8_SB(1, 1), cB + hstep + kstep, voffB);
;         PG8_WAIT_V(6); PG8_BAR;
.LBB0_944:
	s_lshl_b32 s9, s16, 5
	s_add_i32 s58, s2, 0x18000
	s_mov_b64 s[16:17], 0x80
	s_and_b32 s20, s9, 0x60
	v_lshl_add_u64 v[6:7], v[6:7], 0, s[16:17]
	s_mov_b32 m0, s58
	s_add_i32 s59, s2, 0x1a000
	s_lshl_b32 s19, s18, 13
	s_lshl_b32 s22, s20, 7
	s_waitcnt vmcnt(2)
	s_barrier
	global_load_lds_dwordx4 v[6:7], off
	v_lshl_add_u64 v[4:5], v[4:5], 0, s[16:17]
	s_mov_b32 m0, s59
	s_add_i32 s60, s2, 0x8000
	s_add_i32 s61, s2, 0xa000
	global_load_lds_dwordx4 v[4:5], off
	v_lshl_add_u64 v[0:1], v[0:1], 0, s[16:17]
	s_mov_b32 m0, s60
	s_add_u32 s48, s12, 0x40080
	global_load_lds_dwordx4 v[0:1], off
	v_lshl_add_u64 v[0:1], v[2:3], 0, s[16:17]
	s_mov_b32 m0, s61
	s_addc_u32 s49, s13, 0
	s_add_i32 s62, s2, 0x1c000
	global_load_lds_dwordx4 v[0:1], off
	v_lshl_add_u64 v[0:1], s[48:49], 0, v[132:133]
	s_mov_b32 m0, s62
	s_add_i32 s63, s2, 0x1e000
	global_load_lds_dwordx4 v[0:1], off
	v_lshl_add_u64 v[0:1], s[48:49], 0, v[128:129]
	s_mov_b32 m0, s63
	v_lshlrev_b32_e32 v2, 2, v10
	global_load_lds_dwordx4 v[0:1], off
	v_bfe_u32 v1, v10, 4, 2
	v_and_b32_e32 v0, 15, v10
	v_lshlrev_b32_e32 v136, 4, v1
	v_lshl_or_b32 v154, v1, 3, s20
	v_lshlrev_b32_e32 v1, 14, v13
	v_lshl_or_b32 v151, s18, 6, v0
	v_lshl_or_b32 v0, v0, 6, v136
	v_and_b32_e32 v2, 32, v2
	v_and_b32_e32 v1, 0xffff8000, v1
	v_bitop3_b32 v153, v0, s19, v2 bitop3:0xde
	v_bitop3_b32 v0, v0, s22, v2 bitop3:0xde
	v_lshl_add_u32 v1, v12, 11, v1
	v_and_b32_e32 v2, 1, v13
	v_lshl_or_b32 v1, v2, 6, v1
	v_lshl_add_u32 v140, v14, 1, v1
	v_lshlrev_b32_e32 v1, 14, v8
	v_and_b32_e32 v1, 0xffff8000, v1
	s_waitcnt vmcnt(6)
	v_lshl_add_u32 v1, v9, 11, v1
	v_and_b32_e32 v2, 1, v8
	s_cmpk_lt_u32 s7, 0x100
	v_lshl_or_b32 v1, v2, 6, v1
	s_sext_i32_i16 s9, s6
	s_cselect_b64 s[18:19], -1, 0
	v_lshl_add_u64 v[138:139], s[42:43], 0, v[136:137]
	s_ashr_i32 s64, s28, 31
	s_mov_b32 s65, s28
	v_mov_b32_e32 v141, v137
	v_lshl_add_u32 v142, v11, 1, v1
	v_mov_b32_e32 v143, v137
	v_mov_b64_e32 v[144:145], 0x580
	v_mov_b64_e32 v[146:147], 0x57f
	v_or_b32_e32 v155, 0x10000, v0
	v_add_u32_e32 v156, 0x10400, v0
	v_add_u32_e32 v157, 0x10800, v0
	v_add_u32_e32 v158, 0x10c00, v0
	v_or_b32_e32 v159, 0x14000, v0
	v_add_u32_e32 v160, 0x14400, v0
	v_add_u32_e32 v161, 0x14800, v0
	v_add_u32_e32 v162, 0x14c00, v0
	s_add_i32 s66, s2, 0xc000
	s_add_i32 s67, s2, 0xe000
	v_or_b32_e32 v163, 0x18000, v0
	v_add_u32_e32 v164, 0x18400, v0
	v_add_u32_e32 v165, 0x18800, v0
	v_add_u32_e32 v166, 0x18c00, v0
	v_or_b32_e32 v167, 0x1c000, v0
	v_add_u32_e32 v168, 0x1c400, v0
	v_add_u32_e32 v169, 0x1c800, v0
	v_add_u32_e32 v170, 0x1cc00, v0
	v_mbcnt_hi_u32_b32 v171, -1, v226
	s_mov_b32 s20, 0x3a800000
	s_mov_b32 s22, 0x358637bd
	s_mov_b32 s68, 0x800000
	s_movk_i32 s69, 0xb00
	s_barrier
	s_mov_b32 s98, 0
	s_mov_b32 s99, 0
	s_mov_b32 s100, 0
	s_mov_b32 s101, 0
	s_branch .LBB0_947

;     __host__ __device__ bool next(int i, Unit& u) const {
;         const long L = (long)i * G + c; if (L >= nwg) return false;
;         int wgid = (int)L; { const int q = nwg / NXCD, r = nwg % NXCD, xcd = wgid % NXCD, off = wgid / NXCD; wgid = (xcd < r ? xcd * (q + 1) : r * (q + 1) + (xcd - r) * q) + off; }
;         const int nig = WGM * nN, gid = wgid / nig, fm = gid * WGM, gsz = (nM - fm) < WGM ? (nM - fm) : WGM;
;         u.pm = fm + ((wgid % nig) % gsz); u.pn = (wgid % nig) / gsz; return true;
; template <class Epi, class Sched, bool ALIGN_EPI = false, bool SP2 = false, bool F16 = false, bool TOKPERM = false>
; __device__ __forceinline__ void gemm_phase(PG8_LAS unsigned char* lds, const Gemm g, const Sched& S, const Epi& E, int wv) {
;     ...
; #pragma unroll
;         for (int a = 0; a < 2; ++a)
; #pragma unroll
;             for (int b = 0; b < 2; ++b)
; #pragma unroll
;                 for (int m = 0; m < 4; ++m)
; #pragma unroll
;                     for (int n = 0; n < 2; ++n) acc[a][b][m][n] = (f32x4){0.f, 0.f, 0.f, 0.f};
;         cur = nxt; cA = nA; cB = nB; ++ui;
.LBB0_946:
	s_mov_b32 s99, s98
	s_lshr_b32 s101, s100, 11
	s_andn2_b64 vcc, exec, s[6:7]
	s_mov_b32 s9, s48
	s_mov_b32 s8, s50
	s_mov_b64 s[12:13], s[54:55]
	s_mov_b64 s[10:11], s[52:53]
	s_cbranch_vccz .LBB0_956
.LBB0_947:
	s_add_i32 s45, s45, 1
	s_mul_i32 s6, s45, s64
	s_mul_hi_u32 s7, s45, s65
	s_add_i32 s7, s7, s6
	s_mul_i32 s6, s45, s65
	s_add_u32 s52, s6, s26
	s_addc_u32 s53, s7, s3
	s_mov_b32 s98, 0
	s_mov_b32 s100, 0
	s_cmp_lg_u32 s65, 0x100
	s_cbranch_scc1 .Lsplit_gu1b_hd
	s_cmp_lg_u32 s45, 5
	s_cbranch_scc1 .Lsplit_gu1b_hd
	s_and_b32 s52, s26, 127
	s_add_u32 s52, s52, 0x500
	s_mov_b32 s53, 0
	s_mov_b32 s98, 1
	s_bfe_u32 s100, s26, 0x10007
	s_lshl_b32 s100, s100, 18
.Lsplit_gu1b_hd:
	v_cmp_gt_i64_e32 vcc, s[52:53], v[146:147]
	v_cmp_lt_i64_e64 s[6:7], s[52:53], v[144:145]
	s_cbranch_vccnz .LBB0_949
	s_ashr_i32 s48, s52, 31
	s_lshr_b32 s48, s48, 29
	s_add_i32 s48, s52, s48
	s_ashr_i32 s49, s48, 3
	s_and_b32 s48, s48, -8
	s_sub_i32 s48, s52, s48
	s_cmp_lt_i32 s48, 0
	s_cselect_b32 s50, s4, 0xb0
	s_mul_i32 s48, s50, s48
	s_add_i32 s48, s48, s49
	s_mul_hi_i32 s49, s48, 0x2e8ba2e9
	s_lshr_b32 s50, s49, 31
	s_ashr_i32 s49, s49, 5
	s_add_i32 s49, s49, s50
	s_lshl_b32 s50, s49, 3
	s_sub_i32 s51, 64, s50
	s_min_i32 s51, s51, 8
	s_abs_i32 s52, s51
	v_cvt_f32_u32_e32 v0, s52
	s_sub_i32 s54, 0, s52
	s_mulk_i32 s49, 0xb0
	s_sub_i32 s49, s48, s49
	v_rcp_iflag_f32_e32 v0, v0
	s_abs_i32 s48, s49
	s_xor_b32 s53, s49, s51
	s_ashr_i32 s53, s53, 31
	v_mul_f32_e32 v0, 0x4f7ffffe, v0
	v_cvt_u32_f32_e32 v0, v0
	s_nop 0
	v_readfirstlane_b32 s55, v0
	s_mul_i32 s54, s54, s55
	s_mul_hi_u32 s54, s55, s54
	s_add_i32 s55, s55, s54
	s_mul_hi_u32 s54, s48, s55
	s_mul_i32 s55, s54, s52
	s_sub_i32 s48, s48, s55
	s_add_i32 s56, s54, 1
	s_sub_i32 s55, s48, s52
	s_cmp_ge_u32 s48, s52
	s_cselect_b32 s54, s56, s54
	s_cselect_b32 s48, s55, s48
	s_add_i32 s55, s54, 1
	s_cmp_ge_u32 s48, s52
	s_cselect_b32 s48, s55, s54
	s_xor_b32 s48, s48, s53
	s_sub_i32 s48, s48, s53
	s_mul_i32 s51, s48, s51
	s_sub_i32 s49, s49, s51
	s_add_i32 s50, s49, s50
.LBB0_949:
	s_ashr_i32 s51, s50, 31
	s_lshl_b64 s[52:53], s[50:51], 19
	s_add_u32 s52, s40, s52
	s_addc_u32 s53, s41, s53
	s_add_u32 s52, s52, s100
	s_addc_u32 s53, s53, 0
	s_and_b64 s[54:55], s[6:7], exec
	s_cselect_b32 s51, s53, s11
	s_cselect_b32 s70, s52, s10
	s_ashr_i32 s49, s48, 31
	s_lshl_b64 s[54:55], s[48:49], 19
	s_add_u32 s54, s0, s54
	s_addc_u32 s55, s1, s55
	s_and_b64 s[56:57], s[6:7], exec
	s_cselect_b32 s49, s55, s13
	s_cselect_b32 s71, s54, s12
	s_add_u32 s10, s10, 0x40080
	s_addc_u32 s11, s11, 0
	s_add_u32 s72, s12, 0x100
	v_mov_b32_e32 v0, 0
	s_addc_u32 s73, s13, 0
	s_mov_b32 s74, -2
	v_mov_b32_e32 v1, v0
	v_mov_b32_e32 v2, v0
	v_mov_b32_e32 v3, v0
	v_mov_b32_e32 v4, v0
	v_mov_b32_e32 v5, v0
	v_mov_b32_e32 v6, v0
	v_mov_b32_e32 v7, v0
	v_mov_b32_e32 v16, v0
	v_mov_b32_e32 v17, v0
	v_mov_b32_e32 v18, v0
	v_mov_b32_e32 v19, v0
	v_mov_b32_e32 v20, v0
	v_mov_b32_e32 v21, v0
	v_mov_b32_e32 v22, v0
	v_mov_b32_e32 v23, v0
	v_mov_b32_e32 v32, v0
	v_mov_b32_e32 v33, v0
	v_mov_b32_e32 v34, v0
	v_mov_b32_e32 v35, v0
	v_mov_b32_e32 v36, v0
	v_mov_b32_e32 v37, v0
	v_mov_b32_e32 v38, v0
	v_mov_b32_e32 v39, v0
	v_mov_b32_e32 v48, v0
	v_mov_b32_e32 v49, v0
	v_mov_b32_e32 v50, v0
	v_mov_b32_e32 v51, v0
	v_mov_b32_e32 v52, v0
	v_mov_b32_e32 v53, v0
	v_mov_b32_e32 v54, v0
	v_mov_b32_e32 v55, v0
	v_mov_b32_e32 v8, v0
	v_mov_b32_e32 v9, v0
	v_mov_b32_e32 v10, v0
	v_mov_b32_e32 v11, v0
	v_mov_b32_e32 v12, v0
	v_mov_b32_e32 v13, v0
	v_mov_b32_e32 v14, v0
	v_mov_b32_e32 v15, v0
	v_mov_b32_e32 v24, v0
	v_mov_b32_e32 v25, v0
	v_mov_b32_e32 v26, v0
	v_mov_b32_e32 v27, v0
	v_mov_b32_e32 v28, v0
	v_mov_b32_e32 v29, v0
	v_mov_b32_e32 v30, v0
	v_mov_b32_e32 v31, v0
	v_mov_b32_e32 v40, v0
	v_mov_b32_e32 v41, v0
	v_mov_b32_e32 v42, v0
	v_mov_b32_e32 v43, v0
	v_mov_b32_e32 v44, v0
	v_mov_b32_e32 v45, v0
	v_mov_b32_e32 v46, v0
	v_mov_b32_e32 v47, v0
	v_mov_b32_e32 v56, v0
	v_mov_b32_e32 v57, v0
	v_mov_b32_e32 v58, v0
	v_mov_b32_e32 v59, v0
	v_mov_b32_e32 v60, v0
	v_mov_b32_e32 v61, v0
	v_mov_b32_e32 v62, v0
	v_mov_b32_e32 v63, v0
	v_mov_b32_e32 v64, v0
	v_mov_b32_e32 v65, v0
	v_mov_b32_e32 v66, v0
	v_mov_b32_e32 v67, v0
	v_mov_b32_e32 v68, v0
	v_mov_b32_e32 v69, v0
	v_mov_b32_e32 v70, v0
	v_mov_b32_e32 v71, v0
	v_mov_b32_e32 v80, v0
	v_mov_b32_e32 v81, v0
	v_mov_b32_e32 v82, v0
	v_mov_b32_e32 v83, v0
	v_mov_b32_e32 v84, v0
	v_mov_b32_e32 v85, v0
	v_mov_b32_e32 v86, v0
	v_mov_b32_e32 v87, v0
	v_mov_b32_e32 v96, v0
	v_mov_b32_e32 v97, v0
	v_mov_b32_e32 v98, v0
	v_mov_b32_e32 v99, v0
	v_mov_b32_e32 v100, v0
	v_mov_b32_e32 v101, v0
	v_mov_b32_e32 v102, v0
	v_mov_b32_e32 v103, v0
	v_mov_b32_e32 v112, v0
	v_mov_b32_e32 v113, v0
	v_mov_b32_e32 v114, v0
	v_mov_b32_e32 v115, v0
	v_mov_b32_e32 v120, v0
	v_mov_b32_e32 v121, v0
	v_mov_b32_e32 v122, v0
	v_mov_b32_e32 v123, v0
	v_mov_b32_e32 v72, v0
	v_mov_b32_e32 v73, v0
	v_mov_b32_e32 v74, v0
	v_mov_b32_e32 v75, v0
	v_mov_b32_e32 v76, v0
	v_mov_b32_e32 v77, v0
	v_mov_b32_e32 v78, v0
	v_mov_b32_e32 v79, v0
	v_mov_b32_e32 v88, v0
	v_mov_b32_e32 v89, v0
	v_mov_b32_e32 v90, v0
	v_mov_b32_e32 v91, v0
	v_mov_b32_e32 v92, v0
	v_mov_b32_e32 v93, v0
	v_mov_b32_e32 v94, v0
	v_mov_b32_e32 v95, v0
	v_mov_b32_e32 v104, v0
	v_mov_b32_e32 v105, v0
	v_mov_b32_e32 v106, v0
	v_mov_b32_e32 v107, v0
	v_mov_b32_e32 v108, v0
	v_mov_b32_e32 v109, v0
	v_mov_b32_e32 v110, v0
	v_mov_b32_e32 v111, v0
	v_mov_b32_e32 v116, v0
	v_mov_b32_e32 v117, v0
	v_mov_b32_e32 v118, v0
	v_mov_b32_e32 v119, v0
	v_mov_b32_e32 v124, v0
	v_mov_b32_e32 v125, v0
	v_mov_b32_e32 v126, v0
	v_mov_b32_e32 v127, v0
; #define PG8_STAGE(bufoff, gbase, voff) do { _Pragma("unroll") for (int _i = 0; _i < 2; ++_i) \
;         __builtin_amdgcn_global_load_lds((const unsigned*)((const char*)(gbase) + (voff)[_i]), (PG8_LAS unsigned*)(lds + (bufoff) + ldsw + _i * 8192), 16, 0, 0); } while (0)
; #define PG8_LDA(dst, b, h) do { _Pragma("unroll") for (int m = 0; m < 4; ++m) _Pragma("unroll") for (int k = 0; k < 2; ++k) dst[m][k] = *(const PG8_LAS bf16x8*)(lds + PG8_SA(b, h) + aoff + m * 2048 + k * 1024); } while (0)
; #define PG8_LDB(dst, b, h) do { _Pragma("unroll") for (int n = 0; n < 2; ++n) _Pragma("unroll") for (int k = 0; k < 2; ++k) dst[n][k] = *(const PG8_LAS bf16x8*)(lds + PG8_SB(b, h) + boff + n * 2048 + k * 1024); } while (0)
; #define PG8_MMA(ai, bj, At, Bt) do { __builtin_amdgcn_s_setprio(1); _Pragma("unroll") for (int m = 0; m < 4; ++m) _Pragma("unroll") for (int n = 0; n < 2; ++n) _Pragma("unroll") for (int k = 0; k < 2; ++k) \
;         acc[ai][bj][m][n] = mma16<F16>(Bt[n][k], At[m][k], acc[ai][bj][m][n]); __builtin_amdgcn_s_setprio(0); } while (0)
; #define PG8_WAIT_V(n) asm volatile("s_waitcnt vmcnt(" #n ")" ::: "memory")
; #define PG8_BAR __builtin_amdgcn_s_barrier()
; template <class Epi, class Sched, bool ALIGN_EPI = false, bool SP2 = false, bool F16 = false, bool TOKPERM = false>
; __device__ __forceinline__ void gemm_phase(PG8_LAS unsigned char* lds, const Gemm g, const Sched& S, const Epi& E, int wv) {
;     ...
;         for (int t = 0; t < nt; t += 2) {
;             const bool last = (t == nt - 2);
;             const char* a1 = cA + (size_t)(t + 1) * kstep;
;             const char* a2 = last ? nA : cA + (size_t)(t + 2) * kstep; const char* b2 = last ? nB : cB + (size_t)(t + 2) * kstep;
;             const char* a3 = a2 + kstep; const char* b3 = b2 + kstep;
;             if (last && has_next) S.a_ready(nxt);
;             if constexpr (SP2) {
;             PG8_LDB(B0, 0, 0); PG8_LDB(B1, 0, 1); PG8_SCHED; PG8_LDA(At, 0, 0); PG8_STAGE(PG8_SA(1, 1), a1 + hstep, voffA);
;             PG8_WAIT_V(8); PG8_WAIT_L(0); PG8_BAR; PG8_MMA(0, 0, At, B0); PG8_MMA(0, 1, At, B1); PG8_BAR; PG8_SCHED;
;             PG8_LDA(At, 0, 1); PG8_STAGE(PG8_SB(0, 0), b2, voffB); PG8_STAGE(PG8_SB(0, 1), b2 + hstep, voffB); PG8_STAGE(PG8_SA(0, 0), a2, voffA);
;             PG8_WAIT_V(8); PG8_WAIT_L(0); PG8_BAR; PG8_MMA(1, 0, At, B0); PG8_MMA(1, 1, At, B1); PG8_BAR; PG8_SCHED;
.LBB0_950:
	ds_read_b128 v[172:175], v155
	ds_read_b128 v[176:179], v156
	ds_read_b128 v[180:183], v157
	ds_read_b128 v[184:187], v158
	ds_read_b128 v[188:191], v159
	ds_read_b128 v[192:195], v160
	ds_read_b128 v[196:199], v161
	ds_read_b128 v[200:203], v162
	s_add_u32 s12, s10, 0xfffc0080
	s_addc_u32 s13, s11, -1
	s_cmp_eq_u32 s74, 12
	s_cselect_b32 s57, s51, s13
	s_cselect_b32 s56, s70, s12
	s_cselect_b32 s13, s49, s73
	s_cselect_b32 s12, s71, s72
	s_mov_b32 m0, s66
	v_lshl_add_u64 v[148:149], s[10:11], 0, v[140:141]
	ds_read_b128 v[204:207], v153
	ds_read_b128 v[208:211], v153 offset:1024
	ds_read_b128 v[212:215], v153 offset:2048
	ds_read_b128 v[216:219], v153 offset:3072
	ds_read_b128 v[220:223], v153 offset:4096
	ds_read_b128 v[228:231], v153 offset:5120
	ds_read_b128 v[232:235], v153 offset:6144
	ds_read_b128 v[236:239], v153 offset:7168
	global_load_lds_dwordx4 v[148:149], off
	v_lshl_add_u64 v[148:149], s[10:11], 0, v[142:143]
	s_mov_b32 m0, s67
	s_nop 0
	global_load_lds_dwordx4 v[148:149], off
	s_waitcnt vmcnt(8)
	s_waitcnt lgkmcnt(0)
	s_barrier
	s_setprio 1
	s_waitcnt lgkmcnt(0)
	v_mfma_f32_16x16x32_f16 v[124:127], v[172:175], v[204:207], v[124:127]
	v_mfma_f32_16x16x32_f16 v[116:119], v[180:183], v[204:207], v[116:119]
	v_mfma_f32_16x16x32_f16 v[108:111], v[172:175], v[212:215], v[108:111]
	v_mfma_f32_16x16x32_f16 v[104:107], v[180:183], v[212:215], v[104:107]
	v_mfma_f32_16x16x32_f16 v[92:95], v[172:175], v[220:223], v[92:95]
	v_mfma_f32_16x16x32_f16 v[88:91], v[180:183], v[220:223], v[88:91]
	v_mfma_f32_16x16x32_f16 v[76:79], v[172:175], v[232:235], v[76:79]
	v_mfma_f32_16x16x32_f16 v[72:75], v[180:183], v[232:235], v[72:75]
	v_mfma_f32_16x16x32_f16 v[124:127], v[176:179], v[208:211], v[124:127]
	v_mfma_f32_16x16x32_f16 v[116:119], v[184:187], v[208:211], v[116:119]
	v_mfma_f32_16x16x32_f16 v[108:111], v[176:179], v[216:219], v[108:111]
	v_mfma_f32_16x16x32_f16 v[104:107], v[184:187], v[216:219], v[104:107]
	v_mfma_f32_16x16x32_f16 v[92:95], v[176:179], v[228:231], v[92:95]
	v_mfma_f32_16x16x32_f16 v[88:91], v[184:187], v[228:231], v[88:91]
	v_mfma_f32_16x16x32_f16 v[76:79], v[176:179], v[236:239], v[76:79]
	v_mfma_f32_16x16x32_f16 v[72:75], v[184:187], v[236:239], v[72:75]
	s_setprio 0
	s_setprio 1
	v_mfma_f32_16x16x32_f16 v[120:123], v[188:191], v[204:207], v[120:123]
	v_mfma_f32_16x16x32_f16 v[112:115], v[196:199], v[204:207], v[112:115]
	v_mfma_f32_16x16x32_f16 v[100:103], v[188:191], v[212:215], v[100:103]
	v_mfma_f32_16x16x32_f16 v[96:99], v[196:199], v[212:215], v[96:99]
	v_mfma_f32_16x16x32_f16 v[84:87], v[188:191], v[220:223], v[84:87]
	v_mfma_f32_16x16x32_f16 v[80:83], v[196:199], v[220:223], v[80:83]
	v_mfma_f32_16x16x32_f16 v[68:71], v[188:191], v[232:235], v[68:71]
	v_mfma_f32_16x16x32_f16 v[64:67], v[196:199], v[232:235], v[64:67]
	v_mfma_f32_16x16x32_f16 v[120:123], v[192:195], v[208:211], v[120:123]
	v_mfma_f32_16x16x32_f16 v[112:115], v[200:203], v[208:211], v[112:115]
	v_mfma_f32_16x16x32_f16 v[100:103], v[192:195], v[216:219], v[100:103]
	v_mfma_f32_16x16x32_f16 v[96:99], v[200:203], v[216:219], v[96:99]
	v_mfma_f32_16x16x32_f16 v[84:87], v[192:195], v[228:231], v[84:87]
	v_mfma_f32_16x16x32_f16 v[80:83], v[200:203], v[228:231], v[80:83]
	v_mfma_f32_16x16x32_f16 v[68:71], v[192:195], v[236:239], v[68:71]
	v_mfma_f32_16x16x32_f16 v[64:67], v[200:203], v[236:239], v[64:67]
	s_setprio 0
	s_barrier
	s_mov_b32 m0, s5
	v_lshl_add_u64 v[148:149], s[12:13], 0, v[132:133]
	s_add_u32 s76, s12, 0x40000
	ds_read_b128 v[204:207], v153 offset:16384
	ds_read_b128 v[208:211], v153 offset:17408
	ds_read_b128 v[212:215], v153 offset:18432
	ds_read_b128 v[216:219], v153 offset:19456
	ds_read_b128 v[220:223], v153 offset:20480
	ds_read_b128 v[228:231], v153 offset:21504
	ds_read_b128 v[232:235], v153 offset:22528
	ds_read_b128 v[236:239], v153 offset:23552
	global_load_lds_dwordx4 v[148:149], off
	v_lshl_add_u64 v[224:225], s[12:13], 0, v[128:129]
	s_mov_b32 m0, s21
	s_addc_u32 s77, s13, 0
	global_load_lds_dwordx4 v[224:225], off
	v_lshl_add_u64 v[240:241], s[76:77], 0, v[132:133]
	s_mov_b32 m0, s23
	v_lshl_add_u64 v[242:243], s[56:57], 0, v[130:131]
	global_load_lds_dwordx4 v[240:241], off
	v_lshl_add_u64 v[240:241], s[76:77], 0, v[128:129]
	s_mov_b32 m0, s33
	s_nop 0
	global_load_lds_dwordx4 v[240:241], off
	v_lshl_add_u64 v[240:241], s[56:57], 0, v[134:135]
	s_mov_b32 m0, s2
	s_nop 0
	global_load_lds_dwordx4 v[240:241], off
	s_mov_b32 m0, s36
	s_nop 0
	global_load_lds_dwordx4 v[242:243], off
	s_waitcnt vmcnt(8)
	s_waitcnt lgkmcnt(0)
	s_barrier
	s_cmp_lg_u32 s99, 0
	s_cbranch_scc1 .Lsplit_gu1b_k1
	s_setprio 1
	s_waitcnt lgkmcnt(0)
	v_mfma_f32_16x16x32_f16 v[60:63], v[172:175], v[204:207], v[60:63]
	v_mfma_f32_16x16x32_f16 v[56:59], v[180:183], v[204:207], v[56:59]
	v_mfma_f32_16x16x32_f16 v[44:47], v[172:175], v[212:215], v[44:47]
	v_mfma_f32_16x16x32_f16 v[40:43], v[180:183], v[212:215], v[40:43]
	v_mfma_f32_16x16x32_f16 v[28:31], v[172:175], v[220:223], v[28:31]
	v_mfma_f32_16x16x32_f16 v[24:27], v[180:183], v[220:223], v[24:27]
	v_mfma_f32_16x16x32_f16 v[12:15], v[172:175], v[232:235], v[12:15]
	v_mfma_f32_16x16x32_f16 v[8:11], v[180:183], v[232:235], v[8:11]
	v_mfma_f32_16x16x32_f16 v[60:63], v[176:179], v[208:211], v[60:63]
	v_mfma_f32_16x16x32_f16 v[56:59], v[184:187], v[208:211], v[56:59]
	v_mfma_f32_16x16x32_f16 v[44:47], v[176:179], v[216:219], v[44:47]
	v_mfma_f32_16x16x32_f16 v[40:43], v[184:187], v[216:219], v[40:43]
	v_mfma_f32_16x16x32_f16 v[28:31], v[176:179], v[228:231], v[28:31]
	v_mfma_f32_16x16x32_f16 v[24:27], v[184:187], v[228:231], v[24:27]
	v_mfma_f32_16x16x32_f16 v[12:15], v[176:179], v[236:239], v[12:15]
	v_mfma_f32_16x16x32_f16 v[8:11], v[184:187], v[236:239], v[8:11]
	s_setprio 0
	s_setprio 1
	v_mfma_f32_16x16x32_f16 v[52:55], v[188:191], v[204:207], v[52:55]
	v_mfma_f32_16x16x32_f16 v[48:51], v[196:199], v[204:207], v[48:51]
	v_mfma_f32_16x16x32_f16 v[36:39], v[188:191], v[212:215], v[36:39]
	v_mfma_f32_16x16x32_f16 v[32:35], v[196:199], v[212:215], v[32:35]
	v_mfma_f32_16x16x32_f16 v[20:23], v[188:191], v[220:223], v[20:23]
	v_mfma_f32_16x16x32_f16 v[16:19], v[196:199], v[220:223], v[16:19]
	v_mfma_f32_16x16x32_f16 v[4:7], v[188:191], v[232:235], v[4:7]
	v_mfma_f32_16x16x32_f16 v[0:3], v[196:199], v[232:235], v[0:3]
	v_mfma_f32_16x16x32_f16 v[52:55], v[192:195], v[208:211], v[52:55]
	v_mfma_f32_16x16x32_f16 v[48:51], v[200:203], v[208:211], v[48:51]
	v_mfma_f32_16x16x32_f16 v[36:39], v[192:195], v[216:219], v[36:39]
	v_mfma_f32_16x16x32_f16 v[32:35], v[200:203], v[216:219], v[32:35]
	v_mfma_f32_16x16x32_f16 v[20:23], v[192:195], v[228:231], v[20:23]
	v_mfma_f32_16x16x32_f16 v[16:19], v[200:203], v[228:231], v[16:19]
	v_mfma_f32_16x16x32_f16 v[4:7], v[192:195], v[236:239], v[4:7]
	v_mfma_f32_16x16x32_f16 v[0:3], v[200:203], v[236:239], v[0:3]
	s_setprio 0
; #define PG8_STAGE(bufoff, gbase, voff) do { _Pragma("unroll") for (int _i = 0; _i < 2; ++_i) \
;         __builtin_amdgcn_global_load_lds((const unsigned*)((const char*)(gbase) + (voff)[_i]), (PG8_LAS unsigned*)(lds + (bufoff) + ldsw + _i * 8192), 16, 0, 0); } while (0)
; #define PG8_LDA(dst, b, h) do { _Pragma("unroll") for (int m = 0; m < 4; ++m) _Pragma("unroll") for (int k = 0; k < 2; ++k) dst[m][k] = *(const PG8_LAS bf16x8*)(lds + PG8_SA(b, h) + aoff + m * 2048 + k * 1024); } while (0)
; #define PG8_LDB(dst, b, h) do { _Pragma("unroll") for (int n = 0; n < 2; ++n) _Pragma("unroll") for (int k = 0; k < 2; ++k) dst[n][k] = *(const PG8_LAS bf16x8*)(lds + PG8_SB(b, h) + boff + n * 2048 + k * 1024); } while (0)
; #define PG8_MMA(ai, bj, At, Bt) do { __builtin_amdgcn_s_setprio(1); _Pragma("unroll") for (int m = 0; m < 4; ++m) _Pragma("unroll") for (int n = 0; n < 2; ++n) _Pragma("unroll") for (int k = 0; k < 2; ++k) \
;         acc[ai][bj][m][n] = mma16<F16>(Bt[n][k], At[m][k], acc[ai][bj][m][n]); __builtin_amdgcn_s_setprio(0); } while (0)
; #define PG8_WAIT_V(n) asm volatile("s_waitcnt vmcnt(" #n ")" ::: "memory")
; #define PG8_WAIT_L(n) asm volatile("s_waitcnt lgkmcnt(" #n ")" ::: "memory")
; #define PG8_BAR __builtin_amdgcn_s_barrier()
; #define PG8_SCHED __builtin_amdgcn_sched_barrier(0)
; template <class Epi, class Sched, bool ALIGN_EPI = false, bool SP2 = false, bool F16 = false, bool TOKPERM = false>
; __device__ __forceinline__ void gemm_phase(PG8_LAS unsigned char* lds, const Gemm g, const Sched& S, const Epi& E, int wv) {
;     ...
;             PG8_LDB(B0, 1, 0); PG8_LDB(B1, 1, 1); PG8_SCHED; PG8_LDA(At, 1, 0); PG8_STAGE(PG8_SA(0, 1), a2 + hstep, voffA);
;             PG8_WAIT_V(8); PG8_WAIT_L(0); PG8_BAR; PG8_MMA(0, 0, At, B0); PG8_MMA(0, 1, At, B1); PG8_BAR; PG8_SCHED;
;             PG8_LDA(At, 1, 1); PG8_STAGE(PG8_SB(1, 0), b3, voffB); PG8_STAGE(PG8_SB(1, 1), b3 + hstep, voffB); PG8_STAGE(PG8_SA(1, 0), a3, voffA);
;             PG8_WAIT_V(8); PG8_WAIT_L(0); PG8_BAR; PG8_MMA(1, 0, At, B0); PG8_MMA(1, 1, At, B1); PG8_BAR; PG8_SCHED;
.Lsplit_gu1b_k1:
	s_barrier
	ds_read_b128 v[172:175], v163
	ds_read_b128 v[176:179], v164
	ds_read_b128 v[180:183], v165
	ds_read_b128 v[184:187], v166
	ds_read_b128 v[188:191], v167
	ds_read_b128 v[192:195], v168
	ds_read_b128 v[196:199], v169
	ds_read_b128 v[200:203], v170
	s_add_u32 s56, s56, 0x40000
	s_addc_u32 s57, s57, 0
	s_mov_b32 m0, s37
	v_lshl_add_u64 v[244:245], s[56:57], 0, v[134:135]
	ds_read_b128 v[204:207], v153 offset:32768
	ds_read_b128 v[208:211], v153 offset:33792
	ds_read_b128 v[212:215], v153 offset:34816
	ds_read_b128 v[216:219], v153 offset:35840
	ds_read_b128 v[220:223], v153 offset:36864
	ds_read_b128 v[228:231], v153 offset:37888
	ds_read_b128 v[232:235], v153 offset:38912
	ds_read_b128 v[236:239], v153 offset:39936
	global_load_lds_dwordx4 v[244:245], off
	v_lshl_add_u64 v[244:245], s[56:57], 0, v[130:131]
	s_mov_b32 m0, s44
	s_nop 0
	global_load_lds_dwordx4 v[244:245], off
	s_waitcnt vmcnt(8)
	s_waitcnt lgkmcnt(0)
	s_barrier
	s_setprio 1
	s_waitcnt lgkmcnt(0)
	v_mfma_f32_16x16x32_f16 v[124:127], v[172:175], v[204:207], v[124:127]
	v_mfma_f32_16x16x32_f16 v[116:119], v[180:183], v[204:207], v[116:119]
	v_mfma_f32_16x16x32_f16 v[108:111], v[172:175], v[212:215], v[108:111]
	v_mfma_f32_16x16x32_f16 v[104:107], v[180:183], v[212:215], v[104:107]
	v_mfma_f32_16x16x32_f16 v[92:95], v[172:175], v[220:223], v[92:95]
	v_mfma_f32_16x16x32_f16 v[88:91], v[180:183], v[220:223], v[88:91]
	v_mfma_f32_16x16x32_f16 v[76:79], v[172:175], v[232:235], v[76:79]
	v_mfma_f32_16x16x32_f16 v[72:75], v[180:183], v[232:235], v[72:75]
	v_mfma_f32_16x16x32_f16 v[124:127], v[176:179], v[208:211], v[124:127]
	v_mfma_f32_16x16x32_f16 v[116:119], v[184:187], v[208:211], v[116:119]
	v_mfma_f32_16x16x32_f16 v[108:111], v[176:179], v[216:219], v[108:111]
	v_mfma_f32_16x16x32_f16 v[104:107], v[184:187], v[216:219], v[104:107]
	v_mfma_f32_16x16x32_f16 v[92:95], v[176:179], v[228:231], v[92:95]
	v_mfma_f32_16x16x32_f16 v[88:91], v[184:187], v[228:231], v[88:91]
	v_mfma_f32_16x16x32_f16 v[76:79], v[176:179], v[236:239], v[76:79]
	v_mfma_f32_16x16x32_f16 v[72:75], v[184:187], v[236:239], v[72:75]
	s_setprio 0
	s_setprio 1
	v_mfma_f32_16x16x32_f16 v[120:123], v[188:191], v[204:207], v[120:123]
	v_mfma_f32_16x16x32_f16 v[112:115], v[196:199], v[204:207], v[112:115]
	v_mfma_f32_16x16x32_f16 v[100:103], v[188:191], v[212:215], v[100:103]
	v_mfma_f32_16x16x32_f16 v[96:99], v[196:199], v[212:215], v[96:99]
	v_mfma_f32_16x16x32_f16 v[84:87], v[188:191], v[220:223], v[84:87]
	v_mfma_f32_16x16x32_f16 v[80:83], v[196:199], v[220:223], v[80:83]
	v_mfma_f32_16x16x32_f16 v[68:71], v[188:191], v[232:235], v[68:71]
	v_mfma_f32_16x16x32_f16 v[64:67], v[196:199], v[232:235], v[64:67]
	v_mfma_f32_16x16x32_f16 v[120:123], v[192:195], v[208:211], v[120:123]
	v_mfma_f32_16x16x32_f16 v[112:115], v[200:203], v[208:211], v[112:115]
	v_mfma_f32_16x16x32_f16 v[100:103], v[192:195], v[216:219], v[100:103]
	v_mfma_f32_16x16x32_f16 v[96:99], v[200:203], v[216:219], v[96:99]
	v_mfma_f32_16x16x32_f16 v[84:87], v[192:195], v[228:231], v[84:87]
	v_mfma_f32_16x16x32_f16 v[80:83], v[200:203], v[228:231], v[80:83]
	v_mfma_f32_16x16x32_f16 v[68:71], v[192:195], v[236:239], v[68:71]
	v_mfma_f32_16x16x32_f16 v[64:67], v[200:203], v[236:239], v[64:67]
	s_setprio 0
	s_barrier
	s_mov_b32 m0, s58
	v_lshl_add_u64 v[148:149], v[148:149], 0, s[16:17]
	s_add_u32 s12, s12, 0x40080
	ds_read_b128 v[204:207], v153 offset:49152
	ds_read_b128 v[208:211], v153 offset:50176
	ds_read_b128 v[212:215], v153 offset:51200
	ds_read_b128 v[216:219], v153 offset:52224
	ds_read_b128 v[220:223], v153 offset:53248
	ds_read_b128 v[228:231], v153 offset:54272
	ds_read_b128 v[232:235], v153 offset:55296
	ds_read_b128 v[236:239], v153 offset:56320
	global_load_lds_dwordx4 v[148:149], off
	v_lshl_add_u64 v[148:149], v[224:225], 0, s[16:17]
	s_mov_b32 m0, s59
	s_addc_u32 s13, s13, 0
	global_load_lds_dwordx4 v[148:149], off
	v_lshl_add_u64 v[148:149], s[12:13], 0, v[132:133]
	s_mov_b32 m0, s62
	s_nop 0
	global_load_lds_dwordx4 v[148:149], off
	v_lshl_add_u64 v[148:149], s[12:13], 0, v[128:129]
	s_mov_b32 m0, s63
	s_nop 0
	global_load_lds_dwordx4 v[148:149], off
	v_lshl_add_u64 v[148:149], v[240:241], 0, s[16:17]
	s_mov_b32 m0, s60
	s_nop 0
	global_load_lds_dwordx4 v[148:149], off
	v_lshl_add_u64 v[148:149], v[242:243], 0, s[16:17]
	s_mov_b32 m0, s61
	s_nop 0
	global_load_lds_dwordx4 v[148:149], off
	s_waitcnt vmcnt(8)
	s_waitcnt lgkmcnt(0)
	s_barrier
	s_cmp_lg_u32 s99, 0
	s_cbranch_scc1 .Lsplit_gu1b_k0
	s_setprio 1
	s_waitcnt lgkmcnt(0)
	v_mfma_f32_16x16x32_f16 v[60:63], v[172:175], v[204:207], v[60:63]
	v_mfma_f32_16x16x32_f16 v[56:59], v[180:183], v[204:207], v[56:59]
	v_mfma_f32_16x16x32_f16 v[44:47], v[172:175], v[212:215], v[44:47]
	v_mfma_f32_16x16x32_f16 v[40:43], v[180:183], v[212:215], v[40:43]
	v_mfma_f32_16x16x32_f16 v[28:31], v[172:175], v[220:223], v[28:31]
	v_mfma_f32_16x16x32_f16 v[24:27], v[180:183], v[220:223], v[24:27]
	v_mfma_f32_16x16x32_f16 v[12:15], v[172:175], v[232:235], v[12:15]
	v_mfma_f32_16x16x32_f16 v[8:11], v[180:183], v[232:235], v[8:11]
	v_mfma_f32_16x16x32_f16 v[60:63], v[176:179], v[208:211], v[60:63]
	v_mfma_f32_16x16x32_f16 v[56:59], v[184:187], v[208:211], v[56:59]
	v_mfma_f32_16x16x32_f16 v[44:47], v[176:179], v[216:219], v[44:47]
	v_mfma_f32_16x16x32_f16 v[40:43], v[184:187], v[216:219], v[40:43]
	v_mfma_f32_16x16x32_f16 v[28:31], v[176:179], v[228:231], v[28:31]
	v_mfma_f32_16x16x32_f16 v[24:27], v[184:187], v[228:231], v[24:27]
	v_mfma_f32_16x16x32_f16 v[12:15], v[176:179], v[236:239], v[12:15]
	v_mfma_f32_16x16x32_f16 v[8:11], v[184:187], v[236:239], v[8:11]
	s_setprio 0
	s_setprio 1
	v_mfma_f32_16x16x32_f16 v[52:55], v[188:191], v[204:207], v[52:55]
	v_mfma_f32_16x16x32_f16 v[48:51], v[196:199], v[204:207], v[48:51]
	v_mfma_f32_16x16x32_f16 v[36:39], v[188:191], v[212:215], v[36:39]
	v_mfma_f32_16x16x32_f16 v[32:35], v[196:199], v[212:215], v[32:35]
	v_mfma_f32_16x16x32_f16 v[20:23], v[188:191], v[220:223], v[20:23]
	v_mfma_f32_16x16x32_f16 v[16:19], v[196:199], v[220:223], v[16:19]
	v_mfma_f32_16x16x32_f16 v[4:7], v[188:191], v[232:235], v[4:7]
	v_mfma_f32_16x16x32_f16 v[0:3], v[196:199], v[232:235], v[0:3]
	v_mfma_f32_16x16x32_f16 v[52:55], v[192:195], v[208:211], v[52:55]
	v_mfma_f32_16x16x32_f16 v[48:51], v[200:203], v[208:211], v[48:51]
	v_mfma_f32_16x16x32_f16 v[36:39], v[192:195], v[216:219], v[36:39]
	v_mfma_f32_16x16x32_f16 v[32:35], v[200:203], v[216:219], v[32:35]
	v_mfma_f32_16x16x32_f16 v[20:23], v[192:195], v[228:231], v[20:23]
	v_mfma_f32_16x16x32_f16 v[16:19], v[200:203], v[228:231], v[16:19]
	v_mfma_f32_16x16x32_f16 v[4:7], v[192:195], v[236:239], v[4:7]
	v_mfma_f32_16x16x32_f16 v[0:3], v[200:203], v[236:239], v[0:3]
	s_setprio 0
; __device__ __forceinline__ float sigm(float x) { return frcp(1.f + fexp2(-LOG2E * x)); }
;   __device__ __forceinline__ void operator()(const pg8::f32x4 (&acc)[2][2][4][2], const pg8::Unit& u, int wr, int wc, int fr, int fq) const {
;     int z; asm volatile("v_mov_b32 %0, 0" : "=v"(z));
;     const int row0 = u.pm * 256 + wr * 64 + fr + z, col0 = u.pn * 128 + wc * 32 + 8 * fq + z;
; #pragma unroll
;     for (int ai = 0; ai < 2; ++ai) {
;       float rs[4];
; #pragma unroll
;       for (int m = 0; m < 4; ++m) { const f32x4 a = *(const f32x4*)(ssq + (unsigned)(row0 + ai * 128 + m * 16) * 16 + 4 * fq); rs[m] = (a[0] + a[1]) + (a[2] + a[3]); }
; #pragma unroll
;       for (int m = 0; m < 4; ++m) { float v = rs[m]; v += __shfl_xor(v, 16); v += __shfl_xor(v, 32); rs[m] = rsqrtf(v * (1.f / 1024.f) + EPS); }
; #pragma unroll
;       for (int m = 0; m < 4; ++m) {
;         const float r = rs[m]; float v[8];
; #pragma unroll
;         for (int n = 0; n < 2; ++n)
; #pragma unroll
;           for (int c = 0; c < 4; ++c) { const float g = acc[ai][0][m][n][c] * r, uu = acc[ai][1][m][n][c] * r; v[4 * n + c] = g * sigm(g) * uu; }
.Lsplit_gu1b_k0:
	s_barrier
	s_add_i32 s74, s74, 2
	s_add_u32 s10, s10, 0x100
	s_addc_u32 s11, s11, 0
	s_add_u32 s72, s72, 0x100
	s_addc_u32 s73, s73, 0
	s_cmp_gt_u32 s74, 13
	s_cbranch_scc0 .LBB0_950
	s_and_b64 vcc, exec, s[18:19]
	s_cbranch_vccz .LBB0_953
	s_barrier
.LBB0_953:
	s_lshl_b32 s8, s8, 8
	s_add_i32 s8, s8, s101
	v_mov_b32 v150, 0
	v_xor_b32_e32 v173, 32, v171
	v_add3_u32 v190, s8, v151, v150
	v_lshlrev_b32_e32 v136, 4, v190
	v_lshl_add_u64 v[148:149], v[136:137], 2, v[138:139]
	global_load_dwordx4 v[174:177], v[148:149], off
	v_add_u32_e32 v148, 0x100, v136
	v_mov_b32_e32 v149, v137
	v_lshl_add_u64 v[148:149], v[148:149], 2, v[138:139]
	global_load_dwordx4 v[178:181], v[148:149], off
	v_add_u32_e32 v148, 0x200, v136
	v_mov_b32_e32 v149, v137
	v_lshl_add_u64 v[148:149], v[148:149], 2, v[138:139]
	global_load_dwordx4 v[182:185], v[148:149], off
	v_add_u32_e32 v148, 0x300, v136
	v_mov_b32_e32 v149, v137
	v_lshl_add_u64 v[148:149], v[148:149], 2, v[138:139]
	global_load_dwordx4 v[186:189], v[148:149], off
	v_and_b32_e32 v149, 64, v171
	v_xor_b32_e32 v148, 16, v171
	v_add_u32_e32 v191, 64, v149
	v_cmp_lt_i32_e32 vcc, v148, v191
	v_lshl_or_b32 v152, s9, 7, v154
	s_waitcnt vmcnt(0)
	v_mov_b32_e32 v149, v176
	v_cndmask_b32_e32 v148, v171, v148, vcc
	v_lshlrev_b32_e32 v172, 2, v148
	v_mov_b32_e32 v148, v175
	v_mov_b32_e32 v175, v177
	v_pk_add_f32 v[148:149], v[148:149], v[174:175]
	v_mov_b32_e32 v174, v179
	v_mov_b32_e32 v175, v180
	v_mov_b32_e32 v179, v181
	v_mov_b32_e32 v176, v183
	v_mov_b32_e32 v177, v184
	v_mov_b32_e32 v183, v185
	v_mov_b32_e32 v180, v187
	v_mov_b32_e32 v181, v188
	v_mov_b32_e32 v187, v189
	v_pk_add_f32 v[174:175], v[174:175], v[178:179]
	v_pk_add_f32 v[176:177], v[176:177], v[182:183]
	v_pk_add_f32 v[178:179], v[180:181], v[186:187]
	v_mov_b32_e32 v181, v148
	v_mov_b32_e32 v180, v174
	v_mov_b32_e32 v148, v175
	v_mov_b32_e32 v174, v178
	v_mov_b32_e32 v175, v176
	v_mov_b32_e32 v176, v179
	v_pk_add_f32 v[148:149], v[180:181], v[148:149]
	v_pk_add_f32 v[174:175], v[174:175], v[176:177]
	ds_bpermute_b32 v177, v172, v149
	ds_bpermute_b32 v176, v172, v148
	ds_bpermute_b32 v179, v172, v175
	ds_bpermute_b32 v178, v172, v174
	v_cmp_lt_i32_e32 vcc, v173, v191
	v_add_u32_e32 v182, v152, v150
	s_waitcnt lgkmcnt(2)
	v_pk_add_f32 v[176:177], v[148:149], v[176:177]
	v_cndmask_b32_e32 v173, v171, v173, vcc
	v_lshlrev_b32_e32 v173, 2, v173
	s_waitcnt lgkmcnt(0)
	v_pk_add_f32 v[174:175], v[174:175], v[178:179]
	ds_bpermute_b32 v179, v173, v177
	ds_bpermute_b32 v178, v173, v176
	ds_bpermute_b32 v181, v173, v175
	ds_bpermute_b32 v180, v173, v174
	v_mov_b64_e32 v[148:149], s[22:23]
	v_ashrrev_i32_e32 v183, 31, v182
	s_waitcnt lgkmcnt(2)
	v_pk_add_f32 v[176:177], v[176:177], v[178:179]
	s_waitcnt lgkmcnt(0)
	v_pk_add_f32 v[174:175], v[174:175], v[180:181]
	v_pk_fma_f32 v[176:177], v[176:177], s[20:21], v[148:149] op_sel_hi:[1,0,0]
	v_pk_fma_f32 v[174:175], v[174:175], s[20:21], v[148:149] op_sel_hi:[1,0,0]
	v_mul_f32_e32 v150, 0x4b800000, v177
	v_cmp_gt_f32_e32 vcc, s68, v177
	v_mul_f32_e32 v152, 0x4b800000, v176
	v_mul_f32_e32 v178, 0x4b800000, v175
	v_cndmask_b32_e32 v150, v177, v150, vcc
	v_mul_f32_e32 v179, 0x4b800000, v174
	v_cmp_gt_f32_e64 s[8:9], s68, v176
	v_cmp_gt_f32_e64 s[10:11], s68, v175
	v_cmp_gt_f32_e64 s[12:13], s68, v174
	v_rsq_f32_e32 v150, v150
	v_cndmask_b32_e64 v152, v176, v152, s[8:9]
	v_cndmask_b32_e64 v175, v175, v178, s[10:11]
	v_cndmask_b32_e64 v174, v174, v179, s[12:13]
	v_rsq_f32_e32 v152, v152
	v_rsq_f32_e32 v175, v175
	v_rsq_f32_e32 v177, v174
	v_mul_f32_e32 v174, 0x45800000, v150
	v_cndmask_b32_e32 v174, v150, v174, vcc
	v_mul_f32_e32 v176, 0x45800000, v152
	v_mul_f32_e32 v178, 0x45800000, v175
	v_mul_f32_e32 v179, 0x45800000, v177
	v_pk_mul_f32 v[124:125], v[124:125], v[174:175] op_sel_hi:[1,0]
	v_pk_mul_f32 v[126:127], v[126:127], v[174:175] op_sel_hi:[1,0]
	v_cndmask_b32_e64 v176, v152, v176, s[8:9]
	v_cndmask_b32_e64 v152, v175, v178, s[10:11]
	v_cndmask_b32_e64 v150, v177, v179, s[12:13]
	v_pk_mul_f32 v[120:121], v[120:121], v[174:175] op_sel_hi:[1,0]
	v_pk_mul_f32 v[122:123], v[122:123], v[174:175] op_sel_hi:[1,0]
	v_pk_mul_f32 v[116:117], v[116:117], v[174:175] op_sel_hi:[1,0]
	v_mul_f32_e32 v175, 0xbfb8aa3b, v124
	v_mul_f32_e32 v178, 0xbfb8aa3b, v126
	v_mul_f32_e32 v179, 0xbfb8aa3b, v127
	v_exp_f32_e32 v175, v175
	v_exp_f32_e32 v178, v178
	v_exp_f32_e32 v179, v179
	v_mul_f32_e32 v177, 0xbfb8aa3b, v125
	v_mul_f32_e32 v184, 0xbfb8aa3b, v116
	v_exp_f32_e32 v177, v177
	v_add_f32_e32 v175, 1.0, v175
	v_add_f32_e32 v180, 1.0, v178
	v_add_f32_e32 v181, 1.0, v179
	v_rcp_f32_e32 v178, v175
	v_rcp_f32_e32 v180, v180
	v_rcp_f32_e32 v181, v181
	v_exp_f32_e32 v175, v184
	v_add_f32_e32 v177, 1.0, v177
	v_mul_f32_e32 v185, 0xbfb8aa3b, v117
	v_rcp_f32_e32 v179, v177
	v_pk_mul_f32 v[126:127], v[126:127], v[180:181]
	v_pk_mul_f32 v[118:119], v[118:119], v[174:175] op_sel_hi:[1,0]
	v_exp_f32_e32 v177, v185
	v_pk_mul_f32 v[122:123], v[122:123], v[126:127]
	v_mul_f32_e32 v126, 0xbfb8aa3b, v118
	v_mul_f32_e32 v127, 0xbfb8aa3b, v119
	v_exp_f32_e32 v126, v126
	v_exp_f32_e32 v127, v127
	v_pk_mul_f32 v[124:125], v[124:125], v[178:179]
	v_pk_mul_f32 v[112:113], v[112:113], v[174:175] op_sel_hi:[1,0]
	v_pk_mul_f32 v[120:121], v[120:121], v[124:125]
	v_add_f32_e32 v124, 1.0, v175
	v_add_f32_e32 v125, 1.0, v177
	v_rcp_f32_e32 v124, v124
	v_rcp_f32_e32 v125, v125
	v_add_f32_e32 v126, 1.0, v126
	v_add_f32_e32 v127, 1.0, v127
	v_rcp_f32_e32 v126, v126
	v_rcp_f32_e32 v127, v127
	v_pk_mul_f32 v[116:117], v[116:117], v[124:125]
	v_pk_mul_f32 v[114:115], v[114:115], v[174:175] op_sel_hi:[1,0]
	v_pk_mul_f32 v[112:113], v[112:113], v[116:117]
; __device__ __forceinline__ unsigned pk2(float lo, float hi) { f32x2_t v = {lo, hi}; bf16x2_t b = __builtin_convertvector(v, bf16x2_t); return __builtin_bit_cast(unsigned, b); }
; __device__ __forceinline__ float sigm(float x) { return frcp(1.f + fexp2(-LOG2E * x)); }
;   __device__ __forceinline__ void operator()(const pg8::f32x4 (&acc)[2][2][4][2], const pg8::Unit& u, int wr, int wc, int fr, int fq) const {
;     ...
;       for (int m = 0; m < 4; ++m) {
;         const float r = rs[m]; float v[8];
; #pragma unroll
;         for (int n = 0; n < 2; ++n)
; #pragma unroll
;           for (int c = 0; c < 4; ++c) { const float g = acc[ai][0][m][n][c] * r, uu = acc[ai][1][m][n][c] * r; v[4 * n + c] = g * sigm(g) * uu; }
;         u32x4 w; w.x = pk2(v[0], v[1]); w.y = pk2(v[2], v[3]); w.z = pk2(v[4], v[5]); w.w = pk2(v[6], v[7]);
;         *(u32x4*)(hbuf + (unsigned)(row0 + ai * 128 + m * 16) * DFF + col0) = w;
;       }
	v_pk_mul_f32 v[116:117], v[118:119], v[126:127]
	v_cvt_pk_bf16_f32 v118, v112, v113
	v_pk_mul_f32 v[114:115], v[114:115], v[116:117]
	v_cvt_pk_bf16_f32 v116, v120, v121
	v_cvt_pk_bf16_f32 v119, v114, v115
	v_mul_lo_u32 v114, v190, s69
	v_mov_b32_e32 v115, v137
	v_lshl_add_u64 v[120:121], v[114:115], 1, s[38:39]
	v_lshlrev_b64 v[112:113], 1, v[182:183]
	v_pk_mul_f32 v[108:109], v[108:109], v[176:177] op_sel_hi:[1,0]
	v_cvt_pk_bf16_f32 v117, v122, v123
	v_lshl_add_u64 v[120:121], v[120:121], 0, v[112:113]
	v_mul_f32_e32 v115, 0xbfb8aa3b, v108
	v_exp_f32_e32 v115, v115
	global_store_dwordx4 v[120:121], v[116:119], off
	v_pk_mul_f32 v[110:111], v[110:111], v[176:177] op_sel_hi:[1,0]
	v_pk_mul_f32 v[100:101], v[100:101], v[176:177] op_sel_hi:[1,0]
	v_mul_f32_e32 v116, 0xbfb8aa3b, v109
	v_exp_f32_e32 v117, v116
	v_add_f32_e32 v115, 1.0, v115
	v_rcp_f32_e32 v116, v115
	v_pk_mul_f32 v[104:105], v[104:105], v[176:177] op_sel_hi:[1,0]
	v_add_f32_e32 v115, 1.0, v117
	v_mul_f32_e32 v117, 0xbfb8aa3b, v110
	v_exp_f32_e32 v118, v117
	v_mul_f32_e32 v117, 0xbfb8aa3b, v111
	v_exp_f32_e32 v119, v117
	v_rcp_f32_e32 v117, v115
	v_add_f32_e32 v115, 1.0, v118
	v_rcp_f32_e32 v118, v115
	v_add_f32_e32 v115, 1.0, v119
	v_rcp_f32_e32 v119, v115
	v_pk_mul_f32 v[108:109], v[108:109], v[116:117]
	v_pk_mul_f32 v[102:103], v[102:103], v[176:177] op_sel_hi:[1,0]
	v_pk_mul_f32 v[100:101], v[100:101], v[108:109]
	v_pk_mul_f32 v[108:109], v[110:111], v[118:119]
	v_mul_f32_e32 v110, 0xbfb8aa3b, v104
	v_exp_f32_e32 v110, v110
	v_pk_mul_f32 v[102:103], v[102:103], v[108:109]
	v_mul_f32_e32 v108, 0xbfb8aa3b, v105
	v_pk_mul_f32 v[106:107], v[106:107], v[176:177] op_sel_hi:[1,0]
	v_exp_f32_e32 v109, v108
	v_add_f32_e32 v108, 1.0, v110
	v_mul_f32_e32 v110, 0xbfb8aa3b, v106
	v_mul_f32_e32 v111, 0xbfb8aa3b, v107
	v_exp_f32_e32 v110, v110
	v_exp_f32_e32 v111, v111
	v_add_f32_e32 v109, 1.0, v109
	v_rcp_f32_e32 v108, v108
	v_rcp_f32_e32 v109, v109
	v_add_f32_e32 v110, 1.0, v110
	v_add_f32_e32 v111, 1.0, v111
	v_rcp_f32_e32 v110, v110
	v_rcp_f32_e32 v111, v111
	v_pk_mul_f32 v[96:97], v[96:97], v[176:177] op_sel_hi:[1,0]
	v_pk_mul_f32 v[104:105], v[104:105], v[108:109]
	v_pk_mul_f32 v[92:93], v[92:93], v[152:153] op_sel_hi:[1,0]
	v_pk_mul_f32 v[104:105], v[96:97], v[104:105]
	v_pk_mul_f32 v[96:97], v[98:99], v[176:177] op_sel_hi:[1,0]
	v_pk_mul_f32 v[98:99], v[106:107], v[110:111]
	v_pk_mul_f32 v[94:95], v[94:95], v[152:153] op_sel_hi:[1,0]
	v_pk_mul_f32 v[106:107], v[96:97], v[98:99]
	v_cvt_pk_bf16_f32 v96, v100, v101
	v_add_u32_e32 v100, 0xb000, v114
	v_mov_b32_e32 v101, v137
	v_lshl_add_u64 v[100:101], v[100:101], 1, s[38:39]
	v_cvt_pk_bf16_f32 v97, v102, v103
	v_cvt_pk_bf16_f32 v98, v104, v105
	v_cvt_pk_bf16_f32 v99, v106, v107
	v_lshl_add_u64 v[100:101], v[100:101], 0, v[112:113]
	v_mul_f32_e32 v102, 0xbfb8aa3b, v92
	global_store_dwordx4 v[100:101], v[96:99], off
	v_exp_f32_e32 v102, v102
	v_pk_mul_f32 v[84:85], v[84:85], v[152:153] op_sel_hi:[1,0]
	v_mul_f32_e32 v96, 0xbfb8aa3b, v93
	v_exp_f32_e32 v97, v96
	v_mul_f32_e32 v98, 0xbfb8aa3b, v94
	v_mul_f32_e32 v99, 0xbfb8aa3b, v95
	v_exp_f32_e32 v98, v98
	v_exp_f32_e32 v99, v99
	v_add_f32_e32 v96, 1.0, v102
	v_add_f32_e32 v97, 1.0, v97
	v_rcp_f32_e32 v96, v96
	v_rcp_f32_e32 v97, v97
	v_add_f32_e32 v98, 1.0, v98
	v_add_f32_e32 v99, 1.0, v99
	v_rcp_f32_e32 v98, v98
	v_rcp_f32_e32 v99, v99
	v_pk_mul_f32 v[92:93], v[92:93], v[96:97]
	v_pk_mul_f32 v[88:89], v[88:89], v[152:153] op_sel_hi:[1,0]
	v_pk_mul_f32 v[84:85], v[84:85], v[92:93]
	v_pk_mul_f32 v[92:93], v[94:95], v[98:99]
	v_mul_f32_e32 v94, 0xbfb8aa3b, v88
	v_exp_f32_e32 v94, v94
	v_pk_mul_f32 v[86:87], v[86:87], v[152:153] op_sel_hi:[1,0]
	v_pk_mul_f32 v[90:91], v[90:91], v[152:153] op_sel_hi:[1,0]
	v_pk_mul_f32 v[86:87], v[86:87], v[92:93]
	v_mul_f32_e32 v92, 0xbfb8aa3b, v89
	v_exp_f32_e32 v93, v92
	v_add_f32_e32 v92, 1.0, v94
	v_mul_f32_e32 v94, 0xbfb8aa3b, v90
	v_mul_f32_e32 v95, 0xbfb8aa3b, v91
	v_exp_f32_e32 v94, v94
	v_exp_f32_e32 v95, v95
	v_add_f32_e32 v93, 1.0, v93
	v_rcp_f32_e32 v92, v92
	v_rcp_f32_e32 v93, v93
	v_add_f32_e32 v94, 1.0, v94
	v_add_f32_e32 v95, 1.0, v95
	v_rcp_f32_e32 v94, v94
	v_rcp_f32_e32 v95, v95
	v_pk_mul_f32 v[80:81], v[80:81], v[152:153] op_sel_hi:[1,0]
	v_pk_mul_f32 v[88:89], v[88:89], v[92:93]
	v_pk_mul_f32 v[76:77], v[76:77], v[150:151] op_sel_hi:[1,0]
	v_pk_mul_f32 v[88:89], v[80:81], v[88:89]
	v_pk_mul_f32 v[80:81], v[82:83], v[152:153] op_sel_hi:[1,0]
	v_pk_mul_f32 v[82:83], v[90:91], v[94:95]
	v_pk_mul_f32 v[78:79], v[78:79], v[150:151] op_sel_hi:[1,0]
	v_pk_mul_f32 v[90:91], v[80:81], v[82:83]
	v_cvt_pk_bf16_f32 v80, v84, v85
	v_add_u32_e32 v84, 0x16000, v114
	v_mov_b32_e32 v85, v137
	v_lshl_add_u64 v[84:85], v[84:85], 1, s[38:39]
	v_cvt_pk_bf16_f32 v81, v86, v87
	v_cvt_pk_bf16_f32 v82, v88, v89
	v_cvt_pk_bf16_f32 v83, v90, v91
	v_lshl_add_u64 v[84:85], v[84:85], 0, v[112:113]
	v_mul_f32_e32 v86, 0xbfb8aa3b, v76
	global_store_dwordx4 v[84:85], v[80:83], off
	v_exp_f32_e32 v86, v86
	v_pk_mul_f32 v[68:69], v[68:69], v[150:151] op_sel_hi:[1,0]
	v_mul_f32_e32 v80, 0xbfb8aa3b, v77
	v_exp_f32_e32 v81, v80
	v_mul_f32_e32 v82, 0xbfb8aa3b, v78
	v_mul_f32_e32 v83, 0xbfb8aa3b, v79
	v_exp_f32_e32 v82, v82
	v_exp_f32_e32 v83, v83
	v_add_f32_e32 v80, 1.0, v86
	v_add_f32_e32 v81, 1.0, v81
	v_rcp_f32_e32 v80, v80
	v_rcp_f32_e32 v81, v81
	v_add_f32_e32 v82, 1.0, v82
	v_add_f32_e32 v83, 1.0, v83
	v_rcp_f32_e32 v82, v82
	v_rcp_f32_e32 v83, v83
	v_pk_mul_f32 v[76:77], v[76:77], v[80:81]
	v_pk_mul_f32 v[72:73], v[72:73], v[150:151] op_sel_hi:[1,0]
	v_pk_mul_f32 v[68:69], v[68:69], v[76:77]
	v_pk_mul_f32 v[76:77], v[78:79], v[82:83]
	v_mul_f32_e32 v78, 0xbfb8aa3b, v72
	v_exp_f32_e32 v78, v78
	v_pk_mul_f32 v[70:71], v[70:71], v[150:151] op_sel_hi:[1,0]
	v_pk_mul_f32 v[74:75], v[74:75], v[150:151] op_sel_hi:[1,0]
	v_pk_mul_f32 v[70:71], v[70:71], v[76:77]
	v_mul_f32_e32 v76, 0xbfb8aa3b, v73
	v_exp_f32_e32 v77, v76
	v_add_f32_e32 v76, 1.0, v78
	v_mul_f32_e32 v78, 0xbfb8aa3b, v74
	v_mul_f32_e32 v79, 0xbfb8aa3b, v75
	v_exp_f32_e32 v78, v78
	v_exp_f32_e32 v79, v79
	v_add_f32_e32 v77, 1.0, v77
	v_rcp_f32_e32 v76, v76
	v_rcp_f32_e32 v77, v77
	v_add_f32_e32 v78, 1.0, v78
	v_add_f32_e32 v79, 1.0, v79
	v_rcp_f32_e32 v78, v78
	v_rcp_f32_e32 v79, v79
	v_pk_mul_f32 v[64:65], v[64:65], v[150:151] op_sel_hi:[1,0]
	v_pk_mul_f32 v[72:73], v[72:73], v[76:77]
	s_nop 0
	v_pk_mul_f32 v[72:73], v[64:65], v[72:73]
	v_pk_mul_f32 v[64:65], v[66:67], v[150:151] op_sel_hi:[1,0]
	v_pk_mul_f32 v[66:67], v[74:75], v[78:79]
	s_nop 0
	v_pk_mul_f32 v[74:75], v[64:65], v[66:67]
	v_cvt_pk_bf16_f32 v64, v68, v69
	v_add_u32_e32 v68, 0x21000, v114
	v_mov_b32_e32 v69, v137
	v_lshl_add_u64 v[68:69], v[68:69], 1, s[38:39]
	v_cvt_pk_bf16_f32 v65, v70, v71
	v_cvt_pk_bf16_f32 v66, v72, v73
	v_cvt_pk_bf16_f32 v67, v74, v75
	v_lshl_add_u64 v[68:69], v[68:69], 0, v[112:113]
	global_store_dwordx4 v[68:69], v[64:67], off
	s_cmp_lg_u32 s99, 0
	s_cbranch_scc1 .Lsplit_gu1b_tail
; __device__ __forceinline__ unsigned pk2(float lo, float hi) { f32x2_t v = {lo, hi}; bf16x2_t b = __builtin_convertvector(v, bf16x2_t); return __builtin_bit_cast(unsigned, b); }
; __device__ __forceinline__ float sigm(float x) { return frcp(1.f + fexp2(-LOG2E * x)); }
;   __device__ __forceinline__ void operator()(const pg8::f32x4 (&acc)[2][2][4][2], const pg8::Unit& u, int wr, int wc, int fr, int fq) const {
;     ...
;     for (int ai = 0; ai < 2; ++ai) {
;       float rs[4];
; #pragma unroll
;       for (int m = 0; m < 4; ++m) { const f32x4 a = *(const f32x4*)(ssq + (unsigned)(row0 + ai * 128 + m * 16) * 16 + 4 * fq); rs[m] = (a[0] + a[1]) + (a[2] + a[3]); }
; #pragma unroll
;       for (int m = 0; m < 4; ++m) { float v = rs[m]; v += __shfl_xor(v, 16); v += __shfl_xor(v, 32); rs[m] = rsqrtf(v * (1.f / 1024.f) + EPS); }
; #pragma unroll
;       for (int m = 0; m < 4; ++m) {
;         const float r = rs[m]; float v[8];
; #pragma unroll
;         for (int n = 0; n < 2; ++n)
; #pragma unroll
;           for (int c = 0; c < 4; ++c) { const float g = acc[ai][0][m][n][c] * r, uu = acc[ai][1][m][n][c] * r; v[4 * n + c] = g * sigm(g) * uu; }
;         u32x4 w; w.x = pk2(v[0], v[1]); w.y = pk2(v[2], v[3]); w.z = pk2(v[4], v[5]); w.w = pk2(v[6], v[7]);
;         *(u32x4*)(hbuf + (unsigned)(row0 + ai * 128 + m * 16) * DFF + col0) = w;
	v_add_u32_e32 v68, 0x900, v136
	v_mov_b32_e32 v69, v137
	v_add_u32_e32 v64, 0x800, v136
	v_mov_b32_e32 v65, v137
	v_lshl_add_u64 v[64:65], v[64:65], 2, v[138:139]
	v_lshl_add_u64 v[68:69], v[68:69], 2, v[138:139]
	global_load_dwordx4 v[64:67], v[64:65], off
	v_add_u32_e32 v72, 0xa00, v136
	global_load_dwordx4 v[68:71], v[68:69], off
	v_mov_b32_e32 v73, v137
	v_add_u32_e32 v136, 0xb00, v136
	v_lshl_add_u64 v[72:73], v[72:73], 2, v[138:139]
	v_lshl_add_u64 v[76:77], v[136:137], 2, v[138:139]
	global_load_dwordx4 v[72:75], v[72:73], off
	v_add_u32_e32 v136, 0x58000, v114
	global_load_dwordx4 v[76:79], v[76:77], off
	s_waitcnt vmcnt(3)
	v_mov_b32_e32 v80, v65
	v_mov_b32_e32 v81, v66
	v_mov_b32_e32 v65, v67
	s_waitcnt vmcnt(2)
	v_mov_b32_e32 v66, v69
	v_mov_b32_e32 v67, v70
	v_mov_b32_e32 v69, v71
	v_pk_add_f32 v[64:65], v[80:81], v[64:65]
	v_pk_add_f32 v[66:67], v[66:67], v[68:69]
	v_mov_b32_e32 v69, v64
	v_mov_b32_e32 v68, v66
	v_mov_b32_e32 v64, v67
	v_pk_add_f32 v[64:65], v[68:69], v[64:65]
	ds_bpermute_b32 v67, v172, v65
	ds_bpermute_b32 v66, v172, v64
	s_waitcnt vmcnt(1)
	v_mov_b32_e32 v68, v73
	v_mov_b32_e32 v69, v74
	v_mov_b32_e32 v73, v75
	s_waitcnt vmcnt(0)
	v_mov_b32_e32 v70, v77
	s_waitcnt lgkmcnt(0)
	v_pk_add_f32 v[64:65], v[64:65], v[66:67]
	ds_bpermute_b32 v67, v173, v65
	ds_bpermute_b32 v66, v173, v64
	v_mov_b32_e32 v71, v78
	v_mov_b32_e32 v77, v79
	v_pk_add_f32 v[68:69], v[68:69], v[72:73]
	v_pk_add_f32 v[70:71], v[70:71], v[76:77]
	s_waitcnt lgkmcnt(0)
	v_pk_add_f32 v[64:65], v[64:65], v[66:67]
	v_mov_b32_e32 v67, v68
	v_pk_fma_f32 v[64:65], v[64:65], s[20:21], v[148:149] op_sel_hi:[1,0,0]
	v_mov_b32_e32 v68, v71
	v_mul_f32_e32 v66, 0x4b800000, v65
	v_cmp_gt_f32_e32 vcc, s68, v65
	v_cmp_gt_f32_e64 s[8:9], s68, v64
	s_nop 0
	v_cndmask_b32_e32 v65, v65, v66, vcc
	v_mov_b32_e32 v66, v70
	v_pk_add_f32 v[66:67], v[66:67], v[68:69]
	ds_bpermute_b32 v69, v172, v67
	ds_bpermute_b32 v68, v172, v66
	v_rsq_f32_e32 v72, v65
	v_mul_f32_e32 v65, 0x4b800000, v64
	v_cndmask_b32_e64 v64, v64, v65, s[8:9]
	v_rsq_f32_e32 v70, v64
	s_waitcnt lgkmcnt(0)
	v_pk_add_f32 v[64:65], v[66:67], v[68:69]
	ds_bpermute_b32 v67, v173, v65
	ds_bpermute_b32 v66, v173, v64
	v_mul_f32_e32 v68, 0x45800000, v72
	v_cndmask_b32_e32 v68, v72, v68, vcc
	v_mul_f32_e32 v69, 0x45800000, v70
	v_pk_mul_f32 v[62:63], v[62:63], v[68:69] op_sel_hi:[1,0]
	s_waitcnt lgkmcnt(0)
	v_pk_add_f32 v[64:65], v[64:65], v[66:67]
	v_pk_mul_f32 v[56:57], v[56:57], v[68:69] op_sel_hi:[1,0]
	v_pk_fma_f32 v[64:65], v[64:65], s[20:21], v[148:149] op_sel_hi:[1,0,0]
	v_pk_mul_f32 v[54:55], v[54:55], v[68:69] op_sel_hi:[1,0]
	v_mul_f32_e32 v66, 0x4b800000, v65
	v_cmp_gt_f32_e32 vcc, s68, v65
	v_cmp_gt_f32_e64 s[10:11], s68, v64
	v_pk_mul_f32 v[58:59], v[58:59], v[68:69] op_sel_hi:[1,0]
	v_cndmask_b32_e32 v65, v65, v66, vcc
	v_mul_f32_e32 v66, 0x4b800000, v64
	v_rsq_f32_e32 v65, v65
	v_cndmask_b32_e64 v64, v64, v66, s[10:11]
	v_rsq_f32_e32 v67, v64
	v_cndmask_b32_e64 v66, v70, v69, s[8:9]
	v_mul_f32_e32 v64, 0x45800000, v65
	v_pk_mul_f32 v[70:71], v[60:61], v[68:69] op_sel_hi:[1,0]
	v_cndmask_b32_e32 v64, v65, v64, vcc
	v_mul_f32_e32 v65, 0x45800000, v67
	v_mul_f32_e32 v60, 0xbfb8aa3b, v70
	v_exp_f32_e32 v61, v60
	v_cndmask_b32_e64 v60, v67, v65, s[10:11]
	v_mul_f32_e32 v65, 0xbfb8aa3b, v71
	v_exp_f32_e32 v65, v65
	v_add_f32_e32 v61, 1.0, v61
	v_rcp_f32_e32 v72, v61
	v_mul_f32_e32 v67, 0xbfb8aa3b, v63
	v_add_f32_e32 v61, 1.0, v65
	v_mul_f32_e32 v65, 0xbfb8aa3b, v62
	v_exp_f32_e32 v65, v65
	v_exp_f32_e32 v67, v67
	v_rcp_f32_e32 v73, v61
	v_pk_mul_f32 v[52:53], v[52:53], v[68:69] op_sel_hi:[1,0]
	v_add_f32_e32 v61, 1.0, v65
	v_rcp_f32_e32 v74, v61
	v_add_f32_e32 v61, 1.0, v67
	v_rcp_f32_e32 v75, v61
	v_mul_f32_e32 v61, 0xbfb8aa3b, v56
	v_exp_f32_e32 v61, v61
	v_pk_mul_f32 v[70:71], v[70:71], v[72:73]
	v_pk_mul_f32 v[62:63], v[62:63], v[74:75]
	v_pk_mul_f32 v[52:53], v[52:53], v[70:71]
	v_pk_mul_f32 v[54:55], v[54:55], v[62:63]
	v_mul_f32_e32 v62, 0xbfb8aa3b, v57
	v_exp_f32_e32 v63, v62
	v_add_f32_e32 v61, 1.0, v61
	v_rcp_f32_e32 v62, v61
	v_pk_mul_f32 v[48:49], v[48:49], v[68:69] op_sel_hi:[1,0]
	v_add_f32_e32 v61, 1.0, v63
	v_mul_f32_e32 v63, 0xbfb8aa3b, v58
	v_exp_f32_e32 v65, v63
	v_mul_f32_e32 v63, 0xbfb8aa3b, v59
	v_exp_f32_e32 v67, v63
	v_rcp_f32_e32 v63, v61
	v_add_f32_e32 v61, 1.0, v65
	v_rcp_f32_e32 v70, v61
	v_add_f32_e32 v61, 1.0, v67
	v_rcp_f32_e32 v71, v61
	v_pk_mul_f32 v[56:57], v[56:57], v[62:63]
	v_pk_mul_f32 v[44:45], v[44:45], v[66:67] op_sel_hi:[1,0]
	v_pk_mul_f32 v[56:57], v[48:49], v[56:57]
	v_pk_mul_f32 v[48:49], v[50:51], v[68:69] op_sel_hi:[1,0]
	v_pk_mul_f32 v[50:51], v[58:59], v[70:71]
	v_pk_mul_f32 v[46:47], v[46:47], v[66:67] op_sel_hi:[1,0]
	v_pk_mul_f32 v[58:59], v[48:49], v[50:51]
	v_cvt_pk_bf16_f32 v48, v52, v53
	v_lshl_add_u64 v[52:53], v[136:137], 1, s[38:39]
	v_cvt_pk_bf16_f32 v49, v54, v55
	v_cvt_pk_bf16_f32 v50, v56, v57
	v_cvt_pk_bf16_f32 v51, v58, v59
	v_lshl_add_u64 v[52:53], v[52:53], 0, v[112:113]
	v_mul_f32_e32 v54, 0xbfb8aa3b, v44
	global_store_dwordx4 v[52:53], v[48:51], off
	v_exp_f32_e32 v54, v54
	v_pk_mul_f32 v[36:37], v[36:37], v[66:67] op_sel_hi:[1,0]
	v_mul_f32_e32 v48, 0xbfb8aa3b, v45
	v_exp_f32_e32 v49, v48
	v_mul_f32_e32 v50, 0xbfb8aa3b, v46
	v_mul_f32_e32 v51, 0xbfb8aa3b, v47
	v_exp_f32_e32 v50, v50
	v_exp_f32_e32 v51, v51
	v_add_f32_e32 v48, 1.0, v54
	v_add_f32_e32 v49, 1.0, v49
	v_rcp_f32_e32 v48, v48
	v_rcp_f32_e32 v49, v49
	v_add_f32_e32 v50, 1.0, v50
	v_add_f32_e32 v51, 1.0, v51
	v_rcp_f32_e32 v50, v50
	v_rcp_f32_e32 v51, v51
	v_pk_mul_f32 v[44:45], v[44:45], v[48:49]
	v_pk_mul_f32 v[40:41], v[40:41], v[66:67] op_sel_hi:[1,0]
; __device__ __forceinline__ unsigned pk2(float lo, float hi) { f32x2_t v = {lo, hi}; bf16x2_t b = __builtin_convertvector(v, bf16x2_t); return __builtin_bit_cast(unsigned, b); }
; __device__ __forceinline__ float sigm(float x) { return frcp(1.f + fexp2(-LOG2E * x)); }
; #define PG8_BAR __builtin_amdgcn_s_barrier()
; template <class Epi, class Sched, bool ALIGN_EPI = false, bool SP2 = false, bool F16 = false, bool TOKPERM = false>
; __device__ __forceinline__ void gemm_phase(PG8_LAS unsigned char* lds, const Gemm g, const Sched& S, const Epi& E, int wv) {
;     ...
;         if constexpr (!Epi::AFTER_DRAIN) { E(acc, cur, wr, wc, fr, fq); S.done(cur); }
;         if (!has_next) break;
; #pragma unroll
;         for (int a = 0; a < 2; ++a)
; #pragma unroll
;             for (int b = 0; b < 2; ++b)
; #pragma unroll
;                 for (int m = 0; m < 4; ++m)
; #pragma unroll
;                     for (int n = 0; n < 2; ++n) acc[a][b][m][n] = (f32x4){0.f, 0.f, 0.f, 0.f};
;         cur = nxt; cA = nA; cB = nB; ++ui;
;         if constexpr (ALIGN_EPI) { if (wr == 1) PG8_BAR; }
;   __device__ __forceinline__ void operator()(const pg8::f32x4 (&acc)[2][2][4][2], const pg8::Unit& u, int wr, int wc, int fr, int fq) const {
;     ...
;       for (int m = 0; m < 4; ++m) {
;         const float r = rs[m]; float v[8];
; #pragma unroll
;         for (int n = 0; n < 2; ++n)
; #pragma unroll
;           for (int c = 0; c < 4; ++c) { const float g = acc[ai][0][m][n][c] * r, uu = acc[ai][1][m][n][c] * r; v[4 * n + c] = g * sigm(g) * uu; }
;         u32x4 w; w.x = pk2(v[0], v[1]); w.y = pk2(v[2], v[3]); w.z = pk2(v[4], v[5]); w.w = pk2(v[6], v[7]);
;         *(u32x4*)(hbuf + (unsigned)(row0 + ai * 128 + m * 16) * DFF + col0) = w;
;       }
	v_pk_mul_f32 v[36:37], v[36:37], v[44:45]
	v_pk_mul_f32 v[44:45], v[46:47], v[50:51]
	v_mul_f32_e32 v46, 0xbfb8aa3b, v40
	v_exp_f32_e32 v46, v46
	v_pk_mul_f32 v[38:39], v[38:39], v[66:67] op_sel_hi:[1,0]
	v_pk_mul_f32 v[42:43], v[42:43], v[66:67] op_sel_hi:[1,0]
	v_pk_mul_f32 v[38:39], v[38:39], v[44:45]
	v_mul_f32_e32 v44, 0xbfb8aa3b, v41
	v_exp_f32_e32 v45, v44
	v_add_f32_e32 v44, 1.0, v46
	v_mul_f32_e32 v46, 0xbfb8aa3b, v42
	v_mul_f32_e32 v47, 0xbfb8aa3b, v43
	v_exp_f32_e32 v46, v46
	v_exp_f32_e32 v47, v47
	v_add_f32_e32 v45, 1.0, v45
	v_rcp_f32_e32 v44, v44
	v_rcp_f32_e32 v45, v45
	v_add_f32_e32 v46, 1.0, v46
	v_add_f32_e32 v47, 1.0, v47
	v_rcp_f32_e32 v46, v46
	v_rcp_f32_e32 v47, v47
	v_pk_mul_f32 v[32:33], v[32:33], v[66:67] op_sel_hi:[1,0]
	v_pk_mul_f32 v[40:41], v[40:41], v[44:45]
	v_add_u32_e32 v136, 0x63000, v114
	v_pk_mul_f32 v[40:41], v[32:33], v[40:41]
	v_pk_mul_f32 v[32:33], v[34:35], v[66:67] op_sel_hi:[1,0]
	v_pk_mul_f32 v[34:35], v[42:43], v[46:47]
	v_pk_mul_f32 v[28:29], v[28:29], v[64:65] op_sel_hi:[1,0]
	v_pk_mul_f32 v[42:43], v[32:33], v[34:35]
	v_cvt_pk_bf16_f32 v32, v36, v37
	v_lshl_add_u64 v[36:37], v[136:137], 1, s[38:39]
	v_cvt_pk_bf16_f32 v33, v38, v39
	v_cvt_pk_bf16_f32 v34, v40, v41
	v_cvt_pk_bf16_f32 v35, v42, v43
	v_lshl_add_u64 v[36:37], v[36:37], 0, v[112:113]
	v_mul_f32_e32 v38, 0xbfb8aa3b, v28
	global_store_dwordx4 v[36:37], v[32:35], off
	v_pk_mul_f32 v[30:31], v[30:31], v[64:65] op_sel_hi:[1,0]
	v_exp_f32_e32 v38, v38
	v_mul_f32_e32 v32, 0xbfb8aa3b, v29
	v_exp_f32_e32 v33, v32
	v_mul_f32_e32 v34, 0xbfb8aa3b, v30
	v_mul_f32_e32 v35, 0xbfb8aa3b, v31
	v_exp_f32_e32 v34, v34
	v_exp_f32_e32 v35, v35
	v_add_f32_e32 v32, 1.0, v38
	v_add_f32_e32 v33, 1.0, v33
	v_rcp_f32_e32 v32, v32
	v_rcp_f32_e32 v33, v33
	v_add_f32_e32 v34, 1.0, v34
	v_add_f32_e32 v35, 1.0, v35
	v_rcp_f32_e32 v34, v34
	v_rcp_f32_e32 v35, v35
	v_pk_mul_f32 v[20:21], v[20:21], v[64:65] op_sel_hi:[1,0]
	v_pk_mul_f32 v[28:29], v[28:29], v[32:33]
	v_pk_mul_f32 v[24:25], v[24:25], v[64:65] op_sel_hi:[1,0]
	v_pk_mul_f32 v[20:21], v[20:21], v[28:29]
	v_pk_mul_f32 v[28:29], v[30:31], v[34:35]
	v_mul_f32_e32 v30, 0xbfb8aa3b, v24
	v_exp_f32_e32 v30, v30
	v_pk_mul_f32 v[22:23], v[22:23], v[64:65] op_sel_hi:[1,0]
	v_pk_mul_f32 v[26:27], v[26:27], v[64:65] op_sel_hi:[1,0]
	v_pk_mul_f32 v[22:23], v[22:23], v[28:29]
	v_mul_f32_e32 v28, 0xbfb8aa3b, v25
	v_exp_f32_e32 v29, v28
	v_add_f32_e32 v28, 1.0, v30
	v_mul_f32_e32 v30, 0xbfb8aa3b, v26
	v_mul_f32_e32 v31, 0xbfb8aa3b, v27
	v_exp_f32_e32 v30, v30
	v_exp_f32_e32 v31, v31
	v_add_f32_e32 v29, 1.0, v29
	v_rcp_f32_e32 v28, v28
	v_rcp_f32_e32 v29, v29
	v_add_f32_e32 v30, 1.0, v30
	v_add_f32_e32 v31, 1.0, v31
	v_rcp_f32_e32 v30, v30
	v_rcp_f32_e32 v31, v31
	v_pk_mul_f32 v[16:17], v[16:17], v[64:65] op_sel_hi:[1,0]
	v_pk_mul_f32 v[24:25], v[24:25], v[28:29]
	v_add_u32_e32 v136, 0x6e000, v114
	v_pk_mul_f32 v[24:25], v[16:17], v[24:25]
	v_pk_mul_f32 v[16:17], v[18:19], v[64:65] op_sel_hi:[1,0]
	v_pk_mul_f32 v[18:19], v[26:27], v[30:31]
	v_pk_mul_f32 v[12:13], v[12:13], v[60:61] op_sel_hi:[1,0]
	v_pk_mul_f32 v[26:27], v[16:17], v[18:19]
	v_cvt_pk_bf16_f32 v16, v20, v21
	v_lshl_add_u64 v[20:21], v[136:137], 1, s[38:39]
	v_cvt_pk_bf16_f32 v17, v22, v23
	v_cvt_pk_bf16_f32 v18, v24, v25
	v_cvt_pk_bf16_f32 v19, v26, v27
	v_lshl_add_u64 v[20:21], v[20:21], 0, v[112:113]
	v_mul_f32_e32 v22, 0xbfb8aa3b, v12
	global_store_dwordx4 v[20:21], v[16:19], off
	v_pk_mul_f32 v[14:15], v[14:15], v[60:61] op_sel_hi:[1,0]
	v_exp_f32_e32 v22, v22
	v_mul_f32_e32 v16, 0xbfb8aa3b, v13
	v_exp_f32_e32 v17, v16
	v_mul_f32_e32 v18, 0xbfb8aa3b, v14
	v_mul_f32_e32 v19, 0xbfb8aa3b, v15
	v_exp_f32_e32 v18, v18
	v_exp_f32_e32 v19, v19
	v_add_f32_e32 v16, 1.0, v22
	v_add_f32_e32 v17, 1.0, v17
	v_rcp_f32_e32 v16, v16
	v_rcp_f32_e32 v17, v17
	v_add_f32_e32 v18, 1.0, v18
	v_add_f32_e32 v19, 1.0, v19
	v_rcp_f32_e32 v18, v18
	v_rcp_f32_e32 v19, v19
	v_pk_mul_f32 v[4:5], v[4:5], v[60:61] op_sel_hi:[1,0]
	v_pk_mul_f32 v[12:13], v[12:13], v[16:17]
	v_pk_mul_f32 v[8:9], v[8:9], v[60:61] op_sel_hi:[1,0]
	v_pk_mul_f32 v[4:5], v[4:5], v[12:13]
	v_pk_mul_f32 v[12:13], v[14:15], v[18:19]
	v_mul_f32_e32 v14, 0xbfb8aa3b, v8
	v_exp_f32_e32 v14, v14
	v_pk_mul_f32 v[6:7], v[6:7], v[60:61] op_sel_hi:[1,0]
	v_pk_mul_f32 v[10:11], v[10:11], v[60:61] op_sel_hi:[1,0]
	v_pk_mul_f32 v[6:7], v[6:7], v[12:13]
	v_mul_f32_e32 v12, 0xbfb8aa3b, v9
	v_exp_f32_e32 v13, v12
	v_add_f32_e32 v12, 1.0, v14
	v_mul_f32_e32 v14, 0xbfb8aa3b, v10
	v_mul_f32_e32 v15, 0xbfb8aa3b, v11
	v_exp_f32_e32 v14, v14
	v_exp_f32_e32 v15, v15
	v_add_f32_e32 v13, 1.0, v13
	v_rcp_f32_e32 v12, v12
	v_rcp_f32_e32 v13, v13
	v_add_f32_e32 v14, 1.0, v14
	v_add_f32_e32 v15, 1.0, v15
	v_rcp_f32_e32 v14, v14
	v_rcp_f32_e32 v15, v15
	v_pk_mul_f32 v[0:1], v[0:1], v[60:61] op_sel_hi:[1,0]
	v_pk_mul_f32 v[8:9], v[8:9], v[12:13]
	v_add_u32_e32 v136, 0x79000, v114
	v_pk_mul_f32 v[8:9], v[0:1], v[8:9]
	v_pk_mul_f32 v[0:1], v[2:3], v[60:61] op_sel_hi:[1,0]
	v_pk_mul_f32 v[2:3], v[10:11], v[14:15]
	s_andn2_b64 vcc, exec, s[6:7]
	v_pk_mul_f32 v[10:11], v[0:1], v[2:3]
	v_cvt_pk_bf16_f32 v0, v4, v5
	v_lshl_add_u64 v[4:5], v[136:137], 1, s[38:39]
	v_cvt_pk_bf16_f32 v1, v6, v7
	v_cvt_pk_bf16_f32 v2, v8, v9
	v_cvt_pk_bf16_f32 v3, v10, v11
	v_lshl_add_u64 v[4:5], v[4:5], 0, v[112:113]
	global_store_dwordx4 v[4:5], v[0:3], off
	s_mov_b64 s[6:7], -1
	s_cbranch_vccnz .LBB0_946
.Lsplit_gu1b_cont:
	s_andn2_b64 vcc, exec, s[14:15]
	s_cbranch_vccnz .LBB0_945
	s_barrier
	s_branch .LBB0_945
.Lsplit_gu1b_tail:
	s_andn2_b64 vcc, exec, s[6:7]
	s_mov_b64 s[6:7], -1
	s_cbranch_vccnz .LBB0_946
	s_branch .Lsplit_gu1b_cont

; #define PG8_STAGE(bufoff, gbase, voff) do { _Pragma("unroll") for (int _i = 0; _i < 2; ++_i) \
;         __builtin_amdgcn_global_load_lds((const unsigned*)((const char*)(gbase) + (voff)[_i]), (PG8_LAS unsigned*)(lds + (bufoff) + ldsw + _i * 8192), 16, 0, 0); } while (0)
; template <class Epi, class Sched, bool ALIGN_EPI = false, bool SP2 = false, bool F16 = false, bool TOKPERM = false>
; __device__ __forceinline__ void gemm_phase(PG8_LAS unsigned char* lds, const Gemm g, const Sched& S, const Epi& E, int wv) {
;     ...
;     const int tid = tid_, wid = __builtin_amdgcn_readfirstlane(tid >> 6), lane = tid & 63, wr = wid >> 2, wc = wid & 3, fr = lane & 15, fq = lane >> 4;
;     const int K = g.K, nt = K / BK;
;     unsigned voffA[2], voffB[2];
; #pragma unroll
;     for (int i = 0; i < 2; ++i) { int R, C; stage_rc(tid * 16 + i * 8192, R, C); const int Rb = Epi::PERM ? ((R & ~31) + perm32(R & 31)) : R;
;         const int Ra = TOKPERM ? ((R & ~63) + 4 * (R & 15) + ((R >> 4) & 3)) : R;
;         voffA[i] = (unsigned)(Ra * K + C) * 2u; voffB[i] = (unsigned)(Rb * K + C) * 2u; }
;     const size_t kstep = (size_t)(BK * 2);
;     const size_t hstep = (size_t)HALF * K * 2;
;     const size_t tstep = 2 * hstep;
;     const unsigned ldsw = (unsigned)wid * 1024u;
;     const int aoff = lds_byte(wr * 64 + fr, fq * 8), boff = lds_byte(wc * 32 + fr, fq * 8);
;     ...
;     Unit cur, nxt; int ui = 0;
;     if (!S.next(0, cur)) return;
;     f32x4 acc[2][2][4][2];
; #pragma unroll
;     for (int a = 0; a < 2; ++a)
; #pragma unroll
;         for (int b = 0; b < 2; ++b)
; #pragma unroll
;             for (int m = 0; m < 4; ++m)
; #pragma unroll
;                 for (int n = 0; n < 2; ++n) acc[a][b][m][n] = (f32x4){0.f, 0.f, 0.f, 0.f};
;     bf16x8 At[4][2], B0[2][2], B1[2][2];
;     const char* cA = (const char*)g.A + (size_t)cur.pm * tstep; const char* cB = (const char*)g.Bt + (size_t)cur.pn * tstep;
;     S.a_ready(cur);
;     if constexpr (SP2) {
;         PG8_STAGE(PG8_SB(0, 0), cB, voffB); PG8_STAGE(PG8_SB(0, 1), cB + hstep, voffB); PG8_STAGE(PG8_SA(0, 0), cA, voffA); PG8_STAGE(PG8_SA(0, 1), cA + hstep, voffA);
;         if (wr == 1) PG8_BAR;
;         PG8_WAIT_V(2); PG8_BAR;
;         PG8_STAGE(PG8_SB(1, 0), cB + kstep, voffB); PG8_STAGE(PG8_SA(1, 0), cA + kstep, voffA); PG8_STAGE(PG8_SB(1, 1), cB + hstep + kstep, voffB);
;         PG8_WAIT_V(6); PG8_BAR;
.LBB0_1601:
	s_lshl_b32 s7, s14, 5
	s_add_i32 s52, s2, 0x18000
	s_mov_b64 s[14:15], 0x80
	s_and_b32 s18, s7, 0x60
	v_lshl_add_u64 v[6:7], v[6:7], 0, s[14:15]
	s_mov_b32 m0, s52
	s_add_i32 s53, s2, 0x1a000
	s_lshl_b32 s17, s16, 13
	s_lshl_b32 s20, s18, 7
	s_waitcnt vmcnt(2)
	s_barrier
	global_load_lds_dwordx4 v[6:7], off
	v_lshl_add_u64 v[4:5], v[4:5], 0, s[14:15]
	s_mov_b32 m0, s53
	s_add_i32 s54, s2, 0x8000
	s_add_i32 s55, s2, 0xa000
	global_load_lds_dwordx4 v[4:5], off
	v_lshl_add_u64 v[0:1], v[0:1], 0, s[14:15]
	s_mov_b32 m0, s54
	s_add_u32 s22, s10, 0x40080
	global_load_lds_dwordx4 v[0:1], off
	v_lshl_add_u64 v[0:1], v[2:3], 0, s[14:15]
	s_mov_b32 m0, s55
	s_addc_u32 s23, s11, 0
	s_add_i32 s56, s2, 0x1c000
	global_load_lds_dwordx4 v[0:1], off
	v_lshl_add_u64 v[0:1], s[22:23], 0, v[132:133]
	s_mov_b32 m0, s56
	s_add_i32 s57, s2, 0x1e000
	global_load_lds_dwordx4 v[0:1], off
	v_lshl_add_u64 v[0:1], s[22:23], 0, v[128:129]
	s_mov_b32 m0, s57
	v_lshlrev_b32_e32 v2, 2, v10
	global_load_lds_dwordx4 v[0:1], off
	v_bfe_u32 v1, v10, 4, 2
	v_and_b32_e32 v0, 15, v10
	v_lshlrev_b32_e32 v136, 4, v1
	v_lshl_or_b32 v154, v1, 3, s18
	v_lshlrev_b32_e32 v1, 14, v13
	v_lshl_or_b32 v151, s16, 6, v0
	v_lshl_or_b32 v0, v0, 6, v136
	v_and_b32_e32 v2, 32, v2
	v_and_b32_e32 v1, 0xffff8000, v1
	v_bitop3_b32 v153, v0, s17, v2 bitop3:0xde
	v_bitop3_b32 v0, v0, s20, v2 bitop3:0xde
	v_lshl_add_u32 v1, v12, 11, v1
	v_and_b32_e32 v2, 1, v13
	v_lshl_or_b32 v1, v2, 6, v1
	v_lshl_add_u32 v140, v14, 1, v1
	v_lshlrev_b32_e32 v1, 14, v8
	v_and_b32_e32 v1, 0xffff8000, v1
	s_waitcnt vmcnt(6)
	v_lshl_add_u32 v1, v9, 11, v1
	v_and_b32_e32 v2, 1, v8
	s_cmpk_lt_u32 s5, 0x100
	v_lshl_or_b32 v1, v2, 6, v1
	s_sext_i32_i16 s7, s4
	s_cselect_b64 s[16:17], -1, 0
	v_lshl_add_u64 v[138:139], s[42:43], 0, v[136:137]
	s_ashr_i32 s58, s28, 31
	s_mov_b32 s59, s28
	v_mov_b32_e32 v141, v137
	v_lshl_add_u32 v142, v11, 1, v1
	v_mov_b32_e32 v143, v137
	v_mov_b64_e32 v[144:145], 0x580
	v_mov_b64_e32 v[146:147], 0x57f
	v_or_b32_e32 v155, 0x10000, v0
	v_add_u32_e32 v156, 0x10400, v0
	v_add_u32_e32 v157, 0x10800, v0
	v_add_u32_e32 v158, 0x10c00, v0
	v_or_b32_e32 v159, 0x14000, v0
	s_waitcnt vmcnt(0)
	v_add_u32_e32 v160, 0x14400, v0
	v_add_u32_e32 v161, 0x14800, v0
	v_add_u32_e32 v162, 0x14c00, v0
	s_add_i32 s60, s2, 0xc000
	s_add_i32 s61, s2, 0xe000
	v_or_b32_e32 v163, 0x18000, v0
	v_add_u32_e32 v164, 0x18400, v0
	v_add_u32_e32 v165, 0x18800, v0
	v_add_u32_e32 v166, 0x18c00, v0
	v_or_b32_e32 v167, 0x1c000, v0
	v_add_u32_e32 v168, 0x1c400, v0
	v_add_u32_e32 v169, 0x1c800, v0
	v_add_u32_e32 v170, 0x1cc00, v0
	v_mbcnt_hi_u32_b32 v171, -1, v226
	s_mov_b32 s18, 0x3a800000
	s_mov_b32 s20, 0x358637bd
	s_mov_b32 s62, 0x800000
	s_movk_i32 s63, 0xb00
	s_barrier
	s_mov_b32 s98, 0
	s_mov_b32 s99, 0
	s_mov_b32 s100, 0
	s_mov_b32 s101, 0
	s_branch .LBB0_1604

;     __host__ __device__ bool next(int i, Unit& u) const {
;         const long L = (long)i * G + c; if (L >= nwg) return false;
;         int wgid = (int)L; { const int q = nwg / NXCD, r = nwg % NXCD, xcd = wgid % NXCD, off = wgid / NXCD; wgid = (xcd < r ? xcd * (q + 1) : r * (q + 1) + (xcd - r) * q) + off; }
;         const int nig = WGM * nN, gid = wgid / nig, fm = gid * WGM, gsz = (nM - fm) < WGM ? (nM - fm) : WGM;
;         u.pm = fm + ((wgid % nig) % gsz); u.pn = (wgid % nig) / gsz; return true;
; template <class Epi, class Sched, bool ALIGN_EPI = false, bool SP2 = false, bool F16 = false, bool TOKPERM = false>
; __device__ __forceinline__ void gemm_phase(PG8_LAS unsigned char* lds, const Gemm g, const Sched& S, const Epi& E, int wv) {
;     ...
; #pragma unroll
;         for (int a = 0; a < 2; ++a)
; #pragma unroll
;             for (int b = 0; b < 2; ++b)
; #pragma unroll
;                 for (int m = 0; m < 4; ++m)
; #pragma unroll
;                     for (int n = 0; n < 2; ++n) acc[a][b][m][n] = (f32x4){0.f, 0.f, 0.f, 0.f};
;         cur = nxt; cA = nA; cB = nB; ++ui;
.LBB0_1603:
	s_mov_b32 s99, s98
	s_lshr_b32 s101, s100, 11
	s_andn2_b64 vcc, exec, s[4:5]
	s_mov_b32 s7, s22
	s_mov_b32 s6, s24
	s_mov_b64 s[10:11], s[42:43]
	s_mov_b64 s[8:9], s[36:37]
	s_cbranch_vccz .LBB0_1613
.LBB0_1604:
	s_add_i32 s51, s51, 1
	s_mul_i32 s4, s51, s58
	s_mul_hi_u32 s5, s51, s59
	s_add_i32 s5, s5, s4
	s_mul_i32 s4, s51, s59
	s_add_u32 s36, s4, s26
	s_addc_u32 s37, s5, s3
	s_mov_b32 s98, 0
	s_mov_b32 s100, 0
	s_cmp_lg_u32 s59, 0x100
	s_cbranch_scc1 .Lsplit_gu2b_hd
	s_cmp_lg_u32 s51, 5
	s_cbranch_scc1 .Lsplit_gu2b_hd
	s_and_b32 s36, s26, 127
	s_add_u32 s36, s36, 0x500
	s_mov_b32 s37, 0
	s_mov_b32 s98, 1
	s_bfe_u32 s100, s26, 0x10007
	s_lshl_b32 s100, s100, 18
.Lsplit_gu2b_hd:
	v_cmp_gt_i64_e32 vcc, s[36:37], v[146:147]
	v_cmp_lt_i64_e64 s[4:5], s[36:37], v[144:145]
	s_cbranch_vccnz .LBB0_1606
	s_ashr_i32 s22, s36, 31
	s_lshr_b32 s22, s22, 29
	s_add_i32 s22, s36, s22
	s_ashr_i32 s23, s22, 3
	s_and_b32 s22, s22, -8
	s_sub_i32 s22, s36, s22
	s_cmp_lt_i32 s22, 0
	s_cselect_b32 s24, s19, 0xb0
	s_mul_i32 s22, s24, s22
	s_add_i32 s22, s22, s23
	s_mul_hi_i32 s23, s22, 0x2e8ba2e9
	s_lshr_b32 s24, s23, 31
	s_ashr_i32 s23, s23, 5
	s_add_i32 s23, s23, s24
	s_lshl_b32 s24, s23, 3
	s_sub_i32 s25, 64, s24
	s_min_i32 s25, s25, 8
	s_abs_i32 s36, s25
	v_cvt_f32_u32_e32 v0, s36
	s_sub_i32 s42, 0, s36
	s_mulk_i32 s23, 0xb0
	s_sub_i32 s23, s22, s23
	v_rcp_iflag_f32_e32 v0, v0
	s_abs_i32 s22, s23
	s_xor_b32 s37, s23, s25
	s_ashr_i32 s37, s37, 31
	v_mul_f32_e32 v0, 0x4f7ffffe, v0
	v_cvt_u32_f32_e32 v0, v0
	s_nop 0
	v_readfirstlane_b32 s43, v0
	s_mul_i32 s42, s42, s43
	s_mul_hi_u32 s42, s43, s42
	s_add_i32 s43, s43, s42
	s_mul_hi_u32 s42, s22, s43
	s_mul_i32 s43, s42, s36
	s_sub_i32 s22, s22, s43
	s_add_i32 s44, s42, 1
	s_sub_i32 s43, s22, s36
	s_cmp_ge_u32 s22, s36
	s_cselect_b32 s42, s44, s42
	s_cselect_b32 s22, s43, s22
	s_add_i32 s43, s42, 1
	s_cmp_ge_u32 s22, s36
	s_cselect_b32 s22, s43, s42
	s_xor_b32 s22, s22, s37
	s_sub_i32 s22, s22, s37
	s_mul_i32 s25, s22, s25
	s_sub_i32 s23, s23, s25
	s_add_i32 s24, s23, s24
.LBB0_1606:
	s_ashr_i32 s25, s24, 31
	s_lshl_b64 s[36:37], s[24:25], 19
	s_add_u32 s36, s40, s36
	s_addc_u32 s37, s41, s37
	s_add_u32 s36, s36, s100
	s_addc_u32 s37, s37, 0
	s_and_b64 s[42:43], s[4:5], exec
	s_cselect_b32 s25, s37, s9
	s_cselect_b32 s64, s36, s8
	s_ashr_i32 s23, s22, 31
	s_lshl_b64 s[42:43], s[22:23], 19
	s_add_u32 s42, s0, s42
	s_addc_u32 s43, s1, s43
	s_and_b64 s[44:45], s[4:5], exec
	s_cselect_b32 s23, s43, s11
	s_cselect_b32 s65, s42, s10
	s_add_u32 s8, s8, 0x40080
	s_addc_u32 s9, s9, 0
	s_add_u32 s66, s10, 0x100
	v_mov_b32_e32 v0, 0
	s_addc_u32 s67, s11, 0
	s_mov_b32 s68, -2
	v_mov_b32_e32 v1, v0
	v_mov_b32_e32 v2, v0
	v_mov_b32_e32 v3, v0
	v_mov_b32_e32 v4, v0
	v_mov_b32_e32 v5, v0
	v_mov_b32_e32 v6, v0
	v_mov_b32_e32 v7, v0
	v_mov_b32_e32 v16, v0
	v_mov_b32_e32 v17, v0
	v_mov_b32_e32 v18, v0
	v_mov_b32_e32 v19, v0
	v_mov_b32_e32 v20, v0
	v_mov_b32_e32 v21, v0
	v_mov_b32_e32 v22, v0
	v_mov_b32_e32 v23, v0
	v_mov_b32_e32 v32, v0
	v_mov_b32_e32 v33, v0
	v_mov_b32_e32 v34, v0
	v_mov_b32_e32 v35, v0
	v_mov_b32_e32 v36, v0
	v_mov_b32_e32 v37, v0
	v_mov_b32_e32 v38, v0
	v_mov_b32_e32 v39, v0
	v_mov_b32_e32 v48, v0
	v_mov_b32_e32 v49, v0
	v_mov_b32_e32 v50, v0
	v_mov_b32_e32 v51, v0
	v_mov_b32_e32 v52, v0
	v_mov_b32_e32 v53, v0
	v_mov_b32_e32 v54, v0
	v_mov_b32_e32 v55, v0
	v_mov_b32_e32 v8, v0
	v_mov_b32_e32 v9, v0
	v_mov_b32_e32 v10, v0
	v_mov_b32_e32 v11, v0
	v_mov_b32_e32 v12, v0
	v_mov_b32_e32 v13, v0
	v_mov_b32_e32 v14, v0
	v_mov_b32_e32 v15, v0
	v_mov_b32_e32 v24, v0
	v_mov_b32_e32 v25, v0
	v_mov_b32_e32 v26, v0
	v_mov_b32_e32 v27, v0
	v_mov_b32_e32 v28, v0
	v_mov_b32_e32 v29, v0
	v_mov_b32_e32 v30, v0
	v_mov_b32_e32 v31, v0
	v_mov_b32_e32 v40, v0
	v_mov_b32_e32 v41, v0
	v_mov_b32_e32 v42, v0
	v_mov_b32_e32 v43, v0
	v_mov_b32_e32 v44, v0
	v_mov_b32_e32 v45, v0
	v_mov_b32_e32 v46, v0
	v_mov_b32_e32 v47, v0
	v_mov_b32_e32 v56, v0
	v_mov_b32_e32 v57, v0
	v_mov_b32_e32 v58, v0
	v_mov_b32_e32 v59, v0
	v_mov_b32_e32 v60, v0
	v_mov_b32_e32 v61, v0
	v_mov_b32_e32 v62, v0
	v_mov_b32_e32 v63, v0
	v_mov_b32_e32 v64, v0
	v_mov_b32_e32 v65, v0
	v_mov_b32_e32 v66, v0
	v_mov_b32_e32 v67, v0
	v_mov_b32_e32 v68, v0
	v_mov_b32_e32 v69, v0
	v_mov_b32_e32 v70, v0
	v_mov_b32_e32 v71, v0
	v_mov_b32_e32 v80, v0
	v_mov_b32_e32 v81, v0
	v_mov_b32_e32 v82, v0
	v_mov_b32_e32 v83, v0
	v_mov_b32_e32 v84, v0
	v_mov_b32_e32 v85, v0
	v_mov_b32_e32 v86, v0
	v_mov_b32_e32 v87, v0
	v_mov_b32_e32 v96, v0
	v_mov_b32_e32 v97, v0
	v_mov_b32_e32 v98, v0
	v_mov_b32_e32 v99, v0
	v_mov_b32_e32 v100, v0
	v_mov_b32_e32 v101, v0
	v_mov_b32_e32 v102, v0
	v_mov_b32_e32 v103, v0
	v_mov_b32_e32 v112, v0
	v_mov_b32_e32 v113, v0
	v_mov_b32_e32 v114, v0
	v_mov_b32_e32 v115, v0
	v_mov_b32_e32 v120, v0
	v_mov_b32_e32 v121, v0
	v_mov_b32_e32 v122, v0
	v_mov_b32_e32 v123, v0
	v_mov_b32_e32 v72, v0
	v_mov_b32_e32 v73, v0
	v_mov_b32_e32 v74, v0
	v_mov_b32_e32 v75, v0
	v_mov_b32_e32 v76, v0
	v_mov_b32_e32 v77, v0
	v_mov_b32_e32 v78, v0
	v_mov_b32_e32 v79, v0
	v_mov_b32_e32 v88, v0
	v_mov_b32_e32 v89, v0
	v_mov_b32_e32 v90, v0
	v_mov_b32_e32 v91, v0
	v_mov_b32_e32 v92, v0
	v_mov_b32_e32 v93, v0
	v_mov_b32_e32 v94, v0
	v_mov_b32_e32 v95, v0
	v_mov_b32_e32 v104, v0
	v_mov_b32_e32 v105, v0
	v_mov_b32_e32 v106, v0
	v_mov_b32_e32 v107, v0
	v_mov_b32_e32 v108, v0
	v_mov_b32_e32 v109, v0
	v_mov_b32_e32 v110, v0
	v_mov_b32_e32 v111, v0
	v_mov_b32_e32 v116, v0
	v_mov_b32_e32 v117, v0
	v_mov_b32_e32 v118, v0
	v_mov_b32_e32 v119, v0
	v_mov_b32_e32 v124, v0
	v_mov_b32_e32 v125, v0
	v_mov_b32_e32 v126, v0
	v_mov_b32_e32 v127, v0
; #define PG8_STAGE(bufoff, gbase, voff) do { _Pragma("unroll") for (int _i = 0; _i < 2; ++_i) \
;         __builtin_amdgcn_global_load_lds((const unsigned*)((const char*)(gbase) + (voff)[_i]), (PG8_LAS unsigned*)(lds + (bufoff) + ldsw + _i * 8192), 16, 0, 0); } while (0)
; #define PG8_LDA(dst, b, h) do { _Pragma("unroll") for (int m = 0; m < 4; ++m) _Pragma("unroll") for (int k = 0; k < 2; ++k) dst[m][k] = *(const PG8_LAS bf16x8*)(lds + PG8_SA(b, h) + aoff + m * 2048 + k * 1024); } while (0)
; #define PG8_LDB(dst, b, h) do { _Pragma("unroll") for (int n = 0; n < 2; ++n) _Pragma("unroll") for (int k = 0; k < 2; ++k) dst[n][k] = *(const PG8_LAS bf16x8*)(lds + PG8_SB(b, h) + boff + n * 2048 + k * 1024); } while (0)
; #define PG8_MMA(ai, bj, At, Bt) do { __builtin_amdgcn_s_setprio(1); _Pragma("unroll") for (int m = 0; m < 4; ++m) _Pragma("unroll") for (int n = 0; n < 2; ++n) _Pragma("unroll") for (int k = 0; k < 2; ++k) \
;         acc[ai][bj][m][n] = mma16<F16>(Bt[n][k], At[m][k], acc[ai][bj][m][n]); __builtin_amdgcn_s_setprio(0); } while (0)
; #define PG8_WAIT_V(n) asm volatile("s_waitcnt vmcnt(" #n ")" ::: "memory")
; #define PG8_BAR __builtin_amdgcn_s_barrier()
; template <class Epi, class Sched, bool ALIGN_EPI = false, bool SP2 = false, bool F16 = false, bool TOKPERM = false>
; __device__ __forceinline__ void gemm_phase(PG8_LAS unsigned char* lds, const Gemm g, const Sched& S, const Epi& E, int wv) {
;     ...
;         for (int t = 0; t < nt; t += 2) {
;             const bool last = (t == nt - 2);
;             const char* a1 = cA + (size_t)(t + 1) * kstep;
;             const char* a2 = last ? nA : cA + (size_t)(t + 2) * kstep; const char* b2 = last ? nB : cB + (size_t)(t + 2) * kstep;
;             const char* a3 = a2 + kstep; const char* b3 = b2 + kstep;
;             if (last && has_next) S.a_ready(nxt);
;             if constexpr (SP2) {
;             PG8_LDB(B0, 0, 0); PG8_LDB(B1, 0, 1); PG8_SCHED; PG8_LDA(At, 0, 0); PG8_STAGE(PG8_SA(1, 1), a1 + hstep, voffA);
;             PG8_WAIT_V(8); PG8_WAIT_L(0); PG8_BAR; PG8_MMA(0, 0, At, B0); PG8_MMA(0, 1, At, B1); PG8_BAR; PG8_SCHED;
;             PG8_LDA(At, 0, 1); PG8_STAGE(PG8_SB(0, 0), b2, voffB); PG8_STAGE(PG8_SB(0, 1), b2 + hstep, voffB); PG8_STAGE(PG8_SA(0, 0), a2, voffA);
;             PG8_WAIT_V(8); PG8_WAIT_L(0); PG8_BAR; PG8_MMA(1, 0, At, B0); PG8_MMA(1, 1, At, B1); PG8_BAR; PG8_SCHED;
.LBB0_1607:
	ds_read_b128 v[172:175], v155
	ds_read_b128 v[176:179], v156
	ds_read_b128 v[180:183], v157
	ds_read_b128 v[184:187], v158
	ds_read_b128 v[188:191], v159
	ds_read_b128 v[192:195], v160
	ds_read_b128 v[196:199], v161
	ds_read_b128 v[200:203], v162
	s_add_u32 s10, s8, 0xfffc0080
	s_addc_u32 s11, s9, -1
	s_cmp_eq_u32 s68, 12
	s_cselect_b32 s45, s25, s11
	s_cselect_b32 s44, s64, s10
	s_cselect_b32 s11, s23, s67
	s_cselect_b32 s10, s65, s66
	s_mov_b32 m0, s60
	v_lshl_add_u64 v[148:149], s[8:9], 0, v[140:141]
	ds_read_b128 v[204:207], v153
	ds_read_b128 v[208:211], v153 offset:1024
	ds_read_b128 v[212:215], v153 offset:2048
	ds_read_b128 v[216:219], v153 offset:3072
	ds_read_b128 v[220:223], v153 offset:4096
	ds_read_b128 v[224:227], v153 offset:5120
	ds_read_b128 v[228:231], v153 offset:6144
	ds_read_b128 v[232:235], v153 offset:7168
	global_load_lds_dwordx4 v[148:149], off
	v_lshl_add_u64 v[148:149], s[8:9], 0, v[142:143]
	s_mov_b32 m0, s61
	s_nop 0
	global_load_lds_dwordx4 v[148:149], off
	s_waitcnt vmcnt(8)
	s_waitcnt lgkmcnt(0)
	s_barrier
	s_setprio 1
	s_waitcnt lgkmcnt(0)
	v_mfma_f32_16x16x32_f16 v[124:127], v[172:175], v[204:207], v[124:127]
	v_mfma_f32_16x16x32_f16 v[116:119], v[180:183], v[204:207], v[116:119]
	v_mfma_f32_16x16x32_f16 v[108:111], v[172:175], v[212:215], v[108:111]
	v_mfma_f32_16x16x32_f16 v[104:107], v[180:183], v[212:215], v[104:107]
	v_mfma_f32_16x16x32_f16 v[92:95], v[172:175], v[220:223], v[92:95]
	v_mfma_f32_16x16x32_f16 v[88:91], v[180:183], v[220:223], v[88:91]
	v_mfma_f32_16x16x32_f16 v[76:79], v[172:175], v[228:231], v[76:79]
	v_mfma_f32_16x16x32_f16 v[72:75], v[180:183], v[228:231], v[72:75]
	v_mfma_f32_16x16x32_f16 v[124:127], v[176:179], v[208:211], v[124:127]
	v_mfma_f32_16x16x32_f16 v[116:119], v[184:187], v[208:211], v[116:119]
	v_mfma_f32_16x16x32_f16 v[108:111], v[176:179], v[216:219], v[108:111]
	v_mfma_f32_16x16x32_f16 v[104:107], v[184:187], v[216:219], v[104:107]
	v_mfma_f32_16x16x32_f16 v[92:95], v[176:179], v[224:227], v[92:95]
	v_mfma_f32_16x16x32_f16 v[88:91], v[184:187], v[224:227], v[88:91]
	v_mfma_f32_16x16x32_f16 v[76:79], v[176:179], v[232:235], v[76:79]
	v_mfma_f32_16x16x32_f16 v[72:75], v[184:187], v[232:235], v[72:75]
	s_setprio 0
	s_setprio 1
	v_mfma_f32_16x16x32_f16 v[120:123], v[188:191], v[204:207], v[120:123]
	v_mfma_f32_16x16x32_f16 v[112:115], v[196:199], v[204:207], v[112:115]
	v_mfma_f32_16x16x32_f16 v[100:103], v[188:191], v[212:215], v[100:103]
	v_mfma_f32_16x16x32_f16 v[96:99], v[196:199], v[212:215], v[96:99]
	v_mfma_f32_16x16x32_f16 v[84:87], v[188:191], v[220:223], v[84:87]
	v_mfma_f32_16x16x32_f16 v[80:83], v[196:199], v[220:223], v[80:83]
	v_mfma_f32_16x16x32_f16 v[68:71], v[188:191], v[228:231], v[68:71]
	v_mfma_f32_16x16x32_f16 v[64:67], v[196:199], v[228:231], v[64:67]
	v_mfma_f32_16x16x32_f16 v[120:123], v[192:195], v[208:211], v[120:123]
	v_mfma_f32_16x16x32_f16 v[112:115], v[200:203], v[208:211], v[112:115]
	v_mfma_f32_16x16x32_f16 v[100:103], v[192:195], v[216:219], v[100:103]
	v_mfma_f32_16x16x32_f16 v[96:99], v[200:203], v[216:219], v[96:99]
	v_mfma_f32_16x16x32_f16 v[84:87], v[192:195], v[224:227], v[84:87]
	v_mfma_f32_16x16x32_f16 v[80:83], v[200:203], v[224:227], v[80:83]
	v_mfma_f32_16x16x32_f16 v[68:71], v[192:195], v[232:235], v[68:71]
	v_mfma_f32_16x16x32_f16 v[64:67], v[200:203], v[232:235], v[64:67]
	s_setprio 0
	s_barrier
	s_mov_b32 m0, s21
	v_lshl_add_u64 v[148:149], s[10:11], 0, v[132:133]
	s_add_u32 s70, s10, 0x40000
	ds_read_b128 v[204:207], v153 offset:16384
	ds_read_b128 v[208:211], v153 offset:17408
	ds_read_b128 v[212:215], v153 offset:18432
	ds_read_b128 v[216:219], v153 offset:19456
	ds_read_b128 v[220:223], v153 offset:20480
	ds_read_b128 v[224:227], v153 offset:21504
	ds_read_b128 v[228:231], v153 offset:22528
	ds_read_b128 v[232:235], v153 offset:23552
	global_load_lds_dwordx4 v[148:149], off
	v_lshl_add_u64 v[236:237], s[10:11], 0, v[128:129]
	s_mov_b32 m0, s33
	s_addc_u32 s71, s11, 0
	global_load_lds_dwordx4 v[236:237], off
	v_lshl_add_u64 v[238:239], s[70:71], 0, v[132:133]
	s_mov_b32 m0, s46
	v_lshl_add_u64 v[240:241], s[44:45], 0, v[130:131]
	global_load_lds_dwordx4 v[238:239], off
	v_lshl_add_u64 v[238:239], s[70:71], 0, v[128:129]
	s_mov_b32 m0, s47
	s_nop 0
	global_load_lds_dwordx4 v[238:239], off
	v_lshl_add_u64 v[238:239], s[44:45], 0, v[134:135]
	s_mov_b32 m0, s2
	s_nop 0
	global_load_lds_dwordx4 v[238:239], off
	s_mov_b32 m0, s48
	s_nop 0
	global_load_lds_dwordx4 v[240:241], off
	s_waitcnt vmcnt(8)
	s_waitcnt lgkmcnt(0)
	s_barrier
	s_cmp_lg_u32 s99, 0
	s_cbranch_scc1 .Lsplit_gu2b_k1
	s_setprio 1
	s_waitcnt lgkmcnt(0)
	v_mfma_f32_16x16x32_f16 v[60:63], v[172:175], v[204:207], v[60:63]
	v_mfma_f32_16x16x32_f16 v[56:59], v[180:183], v[204:207], v[56:59]
	v_mfma_f32_16x16x32_f16 v[44:47], v[172:175], v[212:215], v[44:47]
	v_mfma_f32_16x16x32_f16 v[40:43], v[180:183], v[212:215], v[40:43]
	v_mfma_f32_16x16x32_f16 v[28:31], v[172:175], v[220:223], v[28:31]
	v_mfma_f32_16x16x32_f16 v[24:27], v[180:183], v[220:223], v[24:27]
	v_mfma_f32_16x16x32_f16 v[12:15], v[172:175], v[228:231], v[12:15]
	v_mfma_f32_16x16x32_f16 v[8:11], v[180:183], v[228:231], v[8:11]
	v_mfma_f32_16x16x32_f16 v[60:63], v[176:179], v[208:211], v[60:63]
	v_mfma_f32_16x16x32_f16 v[56:59], v[184:187], v[208:211], v[56:59]
	v_mfma_f32_16x16x32_f16 v[44:47], v[176:179], v[216:219], v[44:47]
	v_mfma_f32_16x16x32_f16 v[40:43], v[184:187], v[216:219], v[40:43]
	v_mfma_f32_16x16x32_f16 v[28:31], v[176:179], v[224:227], v[28:31]
	v_mfma_f32_16x16x32_f16 v[24:27], v[184:187], v[224:227], v[24:27]
	v_mfma_f32_16x16x32_f16 v[12:15], v[176:179], v[232:235], v[12:15]
	v_mfma_f32_16x16x32_f16 v[8:11], v[184:187], v[232:235], v[8:11]
	s_setprio 0
	s_setprio 1
	v_mfma_f32_16x16x32_f16 v[52:55], v[188:191], v[204:207], v[52:55]
	v_mfma_f32_16x16x32_f16 v[48:51], v[196:199], v[204:207], v[48:51]
	v_mfma_f32_16x16x32_f16 v[36:39], v[188:191], v[212:215], v[36:39]
	v_mfma_f32_16x16x32_f16 v[32:35], v[196:199], v[212:215], v[32:35]
	v_mfma_f32_16x16x32_f16 v[20:23], v[188:191], v[220:223], v[20:23]
	v_mfma_f32_16x16x32_f16 v[16:19], v[196:199], v[220:223], v[16:19]
	v_mfma_f32_16x16x32_f16 v[4:7], v[188:191], v[228:231], v[4:7]
	v_mfma_f32_16x16x32_f16 v[0:3], v[196:199], v[228:231], v[0:3]
	v_mfma_f32_16x16x32_f16 v[52:55], v[192:195], v[208:211], v[52:55]
	v_mfma_f32_16x16x32_f16 v[48:51], v[200:203], v[208:211], v[48:51]
	v_mfma_f32_16x16x32_f16 v[36:39], v[192:195], v[216:219], v[36:39]
	v_mfma_f32_16x16x32_f16 v[32:35], v[200:203], v[216:219], v[32:35]
	v_mfma_f32_16x16x32_f16 v[20:23], v[192:195], v[224:227], v[20:23]
	v_mfma_f32_16x16x32_f16 v[16:19], v[200:203], v[224:227], v[16:19]
	v_mfma_f32_16x16x32_f16 v[4:7], v[192:195], v[232:235], v[4:7]
	v_mfma_f32_16x16x32_f16 v[0:3], v[200:203], v[232:235], v[0:3]
	s_setprio 0
; #define PG8_STAGE(bufoff, gbase, voff) do { _Pragma("unroll") for (int _i = 0; _i < 2; ++_i) \
;         __builtin_amdgcn_global_load_lds((const unsigned*)((const char*)(gbase) + (voff)[_i]), (PG8_LAS unsigned*)(lds + (bufoff) + ldsw + _i * 8192), 16, 0, 0); } while (0)
; #define PG8_LDA(dst, b, h) do { _Pragma("unroll") for (int m = 0; m < 4; ++m) _Pragma("unroll") for (int k = 0; k < 2; ++k) dst[m][k] = *(const PG8_LAS bf16x8*)(lds + PG8_SA(b, h) + aoff + m * 2048 + k * 1024); } while (0)
; #define PG8_LDB(dst, b, h) do { _Pragma("unroll") for (int n = 0; n < 2; ++n) _Pragma("unroll") for (int k = 0; k < 2; ++k) dst[n][k] = *(const PG8_LAS bf16x8*)(lds + PG8_SB(b, h) + boff + n * 2048 + k * 1024); } while (0)
; #define PG8_MMA(ai, bj, At, Bt) do { __builtin_amdgcn_s_setprio(1); _Pragma("unroll") for (int m = 0; m < 4; ++m) _Pragma("unroll") for (int n = 0; n < 2; ++n) _Pragma("unroll") for (int k = 0; k < 2; ++k) \
;         acc[ai][bj][m][n] = mma16<F16>(Bt[n][k], At[m][k], acc[ai][bj][m][n]); __builtin_amdgcn_s_setprio(0); } while (0)
; #define PG8_WAIT_V(n) asm volatile("s_waitcnt vmcnt(" #n ")" ::: "memory")
; #define PG8_WAIT_L(n) asm volatile("s_waitcnt lgkmcnt(" #n ")" ::: "memory")
; #define PG8_BAR __builtin_amdgcn_s_barrier()
; #define PG8_SCHED __builtin_amdgcn_sched_barrier(0)
; template <class Epi, class Sched, bool ALIGN_EPI = false, bool SP2 = false, bool F16 = false, bool TOKPERM = false>
; __device__ __forceinline__ void gemm_phase(PG8_LAS unsigned char* lds, const Gemm g, const Sched& S, const Epi& E, int wv) {
;     ...
;             PG8_LDB(B0, 1, 0); PG8_LDB(B1, 1, 1); PG8_SCHED; PG8_LDA(At, 1, 0); PG8_STAGE(PG8_SA(0, 1), a2 + hstep, voffA);
;             PG8_WAIT_V(8); PG8_WAIT_L(0); PG8_BAR; PG8_MMA(0, 0, At, B0); PG8_MMA(0, 1, At, B1); PG8_BAR; PG8_SCHED;
;             PG8_LDA(At, 1, 1); PG8_STAGE(PG8_SB(1, 0), b3, voffB); PG8_STAGE(PG8_SB(1, 1), b3 + hstep, voffB); PG8_STAGE(PG8_SA(1, 0), a3, voffA);
;             PG8_WAIT_V(8); PG8_WAIT_L(0); PG8_BAR; PG8_MMA(1, 0, At, B0); PG8_MMA(1, 1, At, B1); PG8_BAR; PG8_SCHED;
.Lsplit_gu2b_k1:
	s_barrier
	ds_read_b128 v[172:175], v163
	ds_read_b128 v[176:179], v164
	ds_read_b128 v[180:183], v165
	ds_read_b128 v[184:187], v166
	ds_read_b128 v[188:191], v167
	ds_read_b128 v[192:195], v168
	ds_read_b128 v[196:199], v169
	ds_read_b128 v[200:203], v170
	s_add_u32 s44, s44, 0x40000
	s_addc_u32 s45, s45, 0
	s_mov_b32 m0, s49
	v_lshl_add_u64 v[242:243], s[44:45], 0, v[134:135]
	ds_read_b128 v[204:207], v153 offset:32768
	ds_read_b128 v[208:211], v153 offset:33792
	ds_read_b128 v[212:215], v153 offset:34816
	ds_read_b128 v[216:219], v153 offset:35840
	ds_read_b128 v[220:223], v153 offset:36864
	ds_read_b128 v[224:227], v153 offset:37888
	ds_read_b128 v[228:231], v153 offset:38912
	ds_read_b128 v[232:235], v153 offset:39936
	global_load_lds_dwordx4 v[242:243], off
	v_lshl_add_u64 v[242:243], s[44:45], 0, v[130:131]
	s_mov_b32 m0, s50
	s_nop 0
	global_load_lds_dwordx4 v[242:243], off
	s_waitcnt vmcnt(8)
	s_waitcnt lgkmcnt(0)
	s_barrier
	s_setprio 1
	s_waitcnt lgkmcnt(0)
	v_mfma_f32_16x16x32_f16 v[124:127], v[172:175], v[204:207], v[124:127]
	v_mfma_f32_16x16x32_f16 v[116:119], v[180:183], v[204:207], v[116:119]
	v_mfma_f32_16x16x32_f16 v[108:111], v[172:175], v[212:215], v[108:111]
	v_mfma_f32_16x16x32_f16 v[104:107], v[180:183], v[212:215], v[104:107]
	v_mfma_f32_16x16x32_f16 v[92:95], v[172:175], v[220:223], v[92:95]
	v_mfma_f32_16x16x32_f16 v[88:91], v[180:183], v[220:223], v[88:91]
	v_mfma_f32_16x16x32_f16 v[76:79], v[172:175], v[228:231], v[76:79]
	v_mfma_f32_16x16x32_f16 v[72:75], v[180:183], v[228:231], v[72:75]
	v_mfma_f32_16x16x32_f16 v[124:127], v[176:179], v[208:211], v[124:127]
	v_mfma_f32_16x16x32_f16 v[116:119], v[184:187], v[208:211], v[116:119]
	v_mfma_f32_16x16x32_f16 v[108:111], v[176:179], v[216:219], v[108:111]
	v_mfma_f32_16x16x32_f16 v[104:107], v[184:187], v[216:219], v[104:107]
	v_mfma_f32_16x16x32_f16 v[92:95], v[176:179], v[224:227], v[92:95]
	v_mfma_f32_16x16x32_f16 v[88:91], v[184:187], v[224:227], v[88:91]
	v_mfma_f32_16x16x32_f16 v[76:79], v[176:179], v[232:235], v[76:79]
	v_mfma_f32_16x16x32_f16 v[72:75], v[184:187], v[232:235], v[72:75]
	s_setprio 0
	s_setprio 1
	v_mfma_f32_16x16x32_f16 v[120:123], v[188:191], v[204:207], v[120:123]
	v_mfma_f32_16x16x32_f16 v[112:115], v[196:199], v[204:207], v[112:115]
	v_mfma_f32_16x16x32_f16 v[100:103], v[188:191], v[212:215], v[100:103]
	v_mfma_f32_16x16x32_f16 v[96:99], v[196:199], v[212:215], v[96:99]
	v_mfma_f32_16x16x32_f16 v[84:87], v[188:191], v[220:223], v[84:87]
	v_mfma_f32_16x16x32_f16 v[80:83], v[196:199], v[220:223], v[80:83]
	v_mfma_f32_16x16x32_f16 v[68:71], v[188:191], v[228:231], v[68:71]
	v_mfma_f32_16x16x32_f16 v[64:67], v[196:199], v[228:231], v[64:67]
	v_mfma_f32_16x16x32_f16 v[120:123], v[192:195], v[208:211], v[120:123]
	v_mfma_f32_16x16x32_f16 v[112:115], v[200:203], v[208:211], v[112:115]
	v_mfma_f32_16x16x32_f16 v[100:103], v[192:195], v[216:219], v[100:103]
	v_mfma_f32_16x16x32_f16 v[96:99], v[200:203], v[216:219], v[96:99]
	v_mfma_f32_16x16x32_f16 v[84:87], v[192:195], v[224:227], v[84:87]
	v_mfma_f32_16x16x32_f16 v[80:83], v[200:203], v[224:227], v[80:83]
	v_mfma_f32_16x16x32_f16 v[68:71], v[192:195], v[232:235], v[68:71]
	v_mfma_f32_16x16x32_f16 v[64:67], v[200:203], v[232:235], v[64:67]
	s_setprio 0
	s_barrier
	s_mov_b32 m0, s52
	v_lshl_add_u64 v[148:149], v[148:149], 0, s[14:15]
	s_add_u32 s10, s10, 0x40080
	ds_read_b128 v[204:207], v153 offset:49152
	ds_read_b128 v[208:211], v153 offset:50176
	ds_read_b128 v[212:215], v153 offset:51200
	ds_read_b128 v[216:219], v153 offset:52224
	ds_read_b128 v[220:223], v153 offset:53248
	ds_read_b128 v[224:227], v153 offset:54272
	ds_read_b128 v[228:231], v153 offset:55296
	ds_read_b128 v[232:235], v153 offset:56320
	global_load_lds_dwordx4 v[148:149], off
	v_lshl_add_u64 v[148:149], v[236:237], 0, s[14:15]
	s_mov_b32 m0, s53
	s_addc_u32 s11, s11, 0
	global_load_lds_dwordx4 v[148:149], off
	v_lshl_add_u64 v[148:149], s[10:11], 0, v[132:133]
	s_mov_b32 m0, s56
	s_nop 0
	global_load_lds_dwordx4 v[148:149], off
	v_lshl_add_u64 v[148:149], s[10:11], 0, v[128:129]
	s_mov_b32 m0, s57
	s_nop 0
	global_load_lds_dwordx4 v[148:149], off
	v_lshl_add_u64 v[148:149], v[238:239], 0, s[14:15]
	s_mov_b32 m0, s54
	s_nop 0
	global_load_lds_dwordx4 v[148:149], off
	v_lshl_add_u64 v[148:149], v[240:241], 0, s[14:15]
	s_mov_b32 m0, s55
	s_nop 0
	global_load_lds_dwordx4 v[148:149], off
	s_waitcnt vmcnt(8)
	s_waitcnt lgkmcnt(0)
	s_barrier
	s_cmp_lg_u32 s99, 0
	s_cbranch_scc1 .Lsplit_gu2b_k0
	s_setprio 1
	s_waitcnt lgkmcnt(0)
	v_mfma_f32_16x16x32_f16 v[60:63], v[172:175], v[204:207], v[60:63]
	v_mfma_f32_16x16x32_f16 v[56:59], v[180:183], v[204:207], v[56:59]
	v_mfma_f32_16x16x32_f16 v[44:47], v[172:175], v[212:215], v[44:47]
	v_mfma_f32_16x16x32_f16 v[40:43], v[180:183], v[212:215], v[40:43]
	v_mfma_f32_16x16x32_f16 v[28:31], v[172:175], v[220:223], v[28:31]
	v_mfma_f32_16x16x32_f16 v[24:27], v[180:183], v[220:223], v[24:27]
	v_mfma_f32_16x16x32_f16 v[12:15], v[172:175], v[228:231], v[12:15]
	v_mfma_f32_16x16x32_f16 v[8:11], v[180:183], v[228:231], v[8:11]
	v_mfma_f32_16x16x32_f16 v[60:63], v[176:179], v[208:211], v[60:63]
	v_mfma_f32_16x16x32_f16 v[56:59], v[184:187], v[208:211], v[56:59]
	v_mfma_f32_16x16x32_f16 v[44:47], v[176:179], v[216:219], v[44:47]
	v_mfma_f32_16x16x32_f16 v[40:43], v[184:187], v[216:219], v[40:43]
	v_mfma_f32_16x16x32_f16 v[28:31], v[176:179], v[224:227], v[28:31]
	v_mfma_f32_16x16x32_f16 v[24:27], v[184:187], v[224:227], v[24:27]
	v_mfma_f32_16x16x32_f16 v[12:15], v[176:179], v[232:235], v[12:15]
	v_mfma_f32_16x16x32_f16 v[8:11], v[184:187], v[232:235], v[8:11]
	s_setprio 0
	s_setprio 1
	v_mfma_f32_16x16x32_f16 v[52:55], v[188:191], v[204:207], v[52:55]
	v_mfma_f32_16x16x32_f16 v[48:51], v[196:199], v[204:207], v[48:51]
	v_mfma_f32_16x16x32_f16 v[36:39], v[188:191], v[212:215], v[36:39]
	v_mfma_f32_16x16x32_f16 v[32:35], v[196:199], v[212:215], v[32:35]
	v_mfma_f32_16x16x32_f16 v[20:23], v[188:191], v[220:223], v[20:23]
	v_mfma_f32_16x16x32_f16 v[16:19], v[196:199], v[220:223], v[16:19]
	v_mfma_f32_16x16x32_f16 v[4:7], v[188:191], v[228:231], v[4:7]
	v_mfma_f32_16x16x32_f16 v[0:3], v[196:199], v[228:231], v[0:3]
	v_mfma_f32_16x16x32_f16 v[52:55], v[192:195], v[208:211], v[52:55]
	v_mfma_f32_16x16x32_f16 v[48:51], v[200:203], v[208:211], v[48:51]
	v_mfma_f32_16x16x32_f16 v[36:39], v[192:195], v[216:219], v[36:39]
	v_mfma_f32_16x16x32_f16 v[32:35], v[200:203], v[216:219], v[32:35]
	v_mfma_f32_16x16x32_f16 v[20:23], v[192:195], v[224:227], v[20:23]
	v_mfma_f32_16x16x32_f16 v[16:19], v[200:203], v[224:227], v[16:19]
	v_mfma_f32_16x16x32_f16 v[4:7], v[192:195], v[232:235], v[4:7]
	v_mfma_f32_16x16x32_f16 v[0:3], v[200:203], v[232:235], v[0:3]
	s_setprio 0
; __device__ __forceinline__ float sigm(float x) { return frcp(1.f + fexp2(-LOG2E * x)); }
;   __device__ __forceinline__ void operator()(const pg8::f32x4 (&acc)[2][2][4][2], const pg8::Unit& u, int wr, int wc, int fr, int fq) const {
;     int z; asm volatile("v_mov_b32 %0, 0" : "=v"(z));
;     const int row0 = u.pm * 256 + wr * 64 + fr + z, col0 = u.pn * 128 + wc * 32 + 8 * fq + z;
; #pragma unroll
;     for (int ai = 0; ai < 2; ++ai) {
;       float rs[4];
; #pragma unroll
;       for (int m = 0; m < 4; ++m) { const f32x4 a = *(const f32x4*)(ssq + (unsigned)(row0 + ai * 128 + m * 16) * 16 + 4 * fq); rs[m] = (a[0] + a[1]) + (a[2] + a[3]); }
; #pragma unroll
;       for (int m = 0; m < 4; ++m) { float v = rs[m]; v += __shfl_xor(v, 16); v += __shfl_xor(v, 32); rs[m] = rsqrtf(v * (1.f / 1024.f) + EPS); }
; #pragma unroll
;       for (int m = 0; m < 4; ++m) {
;         const float r = rs[m]; float v[8];
; #pragma unroll
;         for (int n = 0; n < 2; ++n)
; #pragma unroll
;           for (int c = 0; c < 4; ++c) { const float g = acc[ai][0][m][n][c] * r, uu = acc[ai][1][m][n][c] * r; v[4 * n + c] = g * sigm(g) * uu; }
.Lsplit_gu2b_k0:
	s_barrier
	s_add_i32 s68, s68, 2
	s_add_u32 s8, s8, 0x100
	s_addc_u32 s9, s9, 0
	s_add_u32 s66, s66, 0x100
	s_addc_u32 s67, s67, 0
	s_cmp_gt_u32 s68, 13
	s_cbranch_scc0 .LBB0_1607
	s_and_b64 vcc, exec, s[16:17]
	s_cbranch_vccz .LBB0_1610
	s_barrier
.LBB0_1610:
	s_lshl_b32 s6, s6, 8
	s_add_i32 s6, s6, s101
	v_mov_b32 v150, 0
	v_xor_b32_e32 v173, 32, v171
	v_add3_u32 v190, s6, v151, v150
	v_lshlrev_b32_e32 v136, 4, v190
	v_lshl_add_u64 v[148:149], v[136:137], 2, v[138:139]
	global_load_dwordx4 v[174:177], v[148:149], off
	v_add_u32_e32 v148, 0x100, v136
	v_mov_b32_e32 v149, v137
	v_lshl_add_u64 v[148:149], v[148:149], 2, v[138:139]
	global_load_dwordx4 v[178:181], v[148:149], off
	v_add_u32_e32 v148, 0x200, v136
	v_mov_b32_e32 v149, v137
	v_lshl_add_u64 v[148:149], v[148:149], 2, v[138:139]
	global_load_dwordx4 v[182:185], v[148:149], off
	v_add_u32_e32 v148, 0x300, v136
	v_mov_b32_e32 v149, v137
	v_lshl_add_u64 v[148:149], v[148:149], 2, v[138:139]
	global_load_dwordx4 v[186:189], v[148:149], off
	v_and_b32_e32 v149, 64, v171
	v_xor_b32_e32 v148, 16, v171
	v_add_u32_e32 v191, 64, v149
	v_cmp_lt_i32_e32 vcc, v148, v191
	v_lshl_or_b32 v152, s7, 7, v154
	s_waitcnt vmcnt(0)
	v_mov_b32_e32 v149, v176
	v_cndmask_b32_e32 v148, v171, v148, vcc
	v_lshlrev_b32_e32 v172, 2, v148
	v_mov_b32_e32 v148, v175
	v_mov_b32_e32 v175, v177
	v_pk_add_f32 v[148:149], v[148:149], v[174:175]
	v_mov_b32_e32 v174, v179
	v_mov_b32_e32 v175, v180
	v_mov_b32_e32 v179, v181
	v_mov_b32_e32 v176, v183
	v_mov_b32_e32 v177, v184
	v_mov_b32_e32 v183, v185
	v_mov_b32_e32 v180, v187
	v_mov_b32_e32 v181, v188
	v_mov_b32_e32 v187, v189
	v_pk_add_f32 v[174:175], v[174:175], v[178:179]
	v_pk_add_f32 v[176:177], v[176:177], v[182:183]
	v_pk_add_f32 v[178:179], v[180:181], v[186:187]
	v_mov_b32_e32 v181, v148
	v_mov_b32_e32 v180, v174
	v_mov_b32_e32 v148, v175
	v_mov_b32_e32 v174, v178
	v_mov_b32_e32 v175, v176
	v_mov_b32_e32 v176, v179
	v_pk_add_f32 v[148:149], v[180:181], v[148:149]
	v_pk_add_f32 v[174:175], v[174:175], v[176:177]
	ds_bpermute_b32 v177, v172, v149
	ds_bpermute_b32 v176, v172, v148
	ds_bpermute_b32 v179, v172, v175
	ds_bpermute_b32 v178, v172, v174
	v_cmp_lt_i32_e32 vcc, v173, v191
	v_add_u32_e32 v182, v152, v150
	s_waitcnt lgkmcnt(2)
	v_pk_add_f32 v[176:177], v[148:149], v[176:177]
	v_cndmask_b32_e32 v173, v171, v173, vcc
	v_lshlrev_b32_e32 v173, 2, v173
	s_waitcnt lgkmcnt(0)
	v_pk_add_f32 v[174:175], v[174:175], v[178:179]
	ds_bpermute_b32 v179, v173, v177
	ds_bpermute_b32 v178, v173, v176
	ds_bpermute_b32 v181, v173, v175
	ds_bpermute_b32 v180, v173, v174
	v_mov_b64_e32 v[148:149], s[20:21]
	v_ashrrev_i32_e32 v183, 31, v182
	s_waitcnt lgkmcnt(2)
	v_pk_add_f32 v[176:177], v[176:177], v[178:179]
	s_waitcnt lgkmcnt(0)
	v_pk_add_f32 v[174:175], v[174:175], v[180:181]
	v_pk_fma_f32 v[176:177], v[176:177], s[18:19], v[148:149] op_sel_hi:[1,0,0]
	v_pk_fma_f32 v[174:175], v[174:175], s[18:19], v[148:149] op_sel_hi:[1,0,0]
	v_mul_f32_e32 v150, 0x4b800000, v177
	v_cmp_gt_f32_e32 vcc, s62, v177
	v_mul_f32_e32 v152, 0x4b800000, v176
	v_mul_f32_e32 v178, 0x4b800000, v175
	v_cndmask_b32_e32 v150, v177, v150, vcc
	v_mul_f32_e32 v179, 0x4b800000, v174
	v_cmp_gt_f32_e64 s[6:7], s62, v176
	v_cmp_gt_f32_e64 s[8:9], s62, v175
	v_cmp_gt_f32_e64 s[10:11], s62, v174
	v_rsq_f32_e32 v150, v150
	v_cndmask_b32_e64 v152, v176, v152, s[6:7]
	v_cndmask_b32_e64 v175, v175, v178, s[8:9]
	v_cndmask_b32_e64 v174, v174, v179, s[10:11]
	v_rsq_f32_e32 v152, v152
	v_rsq_f32_e32 v175, v175
	v_rsq_f32_e32 v177, v174
	v_mul_f32_e32 v174, 0x45800000, v150
	v_cndmask_b32_e32 v174, v150, v174, vcc
	v_mul_f32_e32 v176, 0x45800000, v152
	v_mul_f32_e32 v178, 0x45800000, v175
	v_mul_f32_e32 v179, 0x45800000, v177
	v_pk_mul_f32 v[124:125], v[124:125], v[174:175] op_sel_hi:[1,0]
	v_pk_mul_f32 v[126:127], v[126:127], v[174:175] op_sel_hi:[1,0]
	v_cndmask_b32_e64 v176, v152, v176, s[6:7]
	v_cndmask_b32_e64 v152, v175, v178, s[8:9]
	v_cndmask_b32_e64 v150, v177, v179, s[10:11]
	v_pk_mul_f32 v[120:121], v[120:121], v[174:175] op_sel_hi:[1,0]
	v_pk_mul_f32 v[122:123], v[122:123], v[174:175] op_sel_hi:[1,0]
	v_pk_mul_f32 v[116:117], v[116:117], v[174:175] op_sel_hi:[1,0]
	v_mul_f32_e32 v175, 0xbfb8aa3b, v124
	v_mul_f32_e32 v178, 0xbfb8aa3b, v126
	v_mul_f32_e32 v179, 0xbfb8aa3b, v127
	v_exp_f32_e32 v175, v175
	v_exp_f32_e32 v178, v178
	v_exp_f32_e32 v179, v179
	v_mul_f32_e32 v177, 0xbfb8aa3b, v125
	v_mul_f32_e32 v184, 0xbfb8aa3b, v116
	v_exp_f32_e32 v177, v177
	v_add_f32_e32 v175, 1.0, v175
	v_add_f32_e32 v180, 1.0, v178
	v_add_f32_e32 v181, 1.0, v179
	v_rcp_f32_e32 v178, v175
	v_rcp_f32_e32 v180, v180
	v_rcp_f32_e32 v181, v181
	v_exp_f32_e32 v175, v184
	v_add_f32_e32 v177, 1.0, v177
	v_mul_f32_e32 v185, 0xbfb8aa3b, v117
	v_rcp_f32_e32 v179, v177
	v_pk_mul_f32 v[126:127], v[126:127], v[180:181]
	v_pk_mul_f32 v[118:119], v[118:119], v[174:175] op_sel_hi:[1,0]
	v_exp_f32_e32 v177, v185
	v_pk_mul_f32 v[122:123], v[122:123], v[126:127]
	v_mul_f32_e32 v126, 0xbfb8aa3b, v118
	v_mul_f32_e32 v127, 0xbfb8aa3b, v119
	v_exp_f32_e32 v126, v126
	v_exp_f32_e32 v127, v127
	v_pk_mul_f32 v[124:125], v[124:125], v[178:179]
	v_pk_mul_f32 v[112:113], v[112:113], v[174:175] op_sel_hi:[1,0]
	v_pk_mul_f32 v[120:121], v[120:121], v[124:125]
	v_add_f32_e32 v124, 1.0, v175
	v_add_f32_e32 v125, 1.0, v177
	v_rcp_f32_e32 v124, v124
	v_rcp_f32_e32 v125, v125
	v_add_f32_e32 v126, 1.0, v126
	v_add_f32_e32 v127, 1.0, v127
	v_rcp_f32_e32 v126, v126
	v_rcp_f32_e32 v127, v127
	v_pk_mul_f32 v[116:117], v[116:117], v[124:125]
	v_pk_mul_f32 v[114:115], v[114:115], v[174:175] op_sel_hi:[1,0]
	v_pk_mul_f32 v[112:113], v[112:113], v[116:117]
; __device__ __forceinline__ unsigned pk2(float lo, float hi) { f32x2_t v = {lo, hi}; bf16x2_t b = __builtin_convertvector(v, bf16x2_t); return __builtin_bit_cast(unsigned, b); }
; __device__ __forceinline__ float sigm(float x) { return frcp(1.f + fexp2(-LOG2E * x)); }
;   __device__ __forceinline__ void operator()(const pg8::f32x4 (&acc)[2][2][4][2], const pg8::Unit& u, int wr, int wc, int fr, int fq) const {
;     ...
;       for (int m = 0; m < 4; ++m) {
;         const float r = rs[m]; float v[8];
; #pragma unroll
;         for (int n = 0; n < 2; ++n)
; #pragma unroll
;           for (int c = 0; c < 4; ++c) { const float g = acc[ai][0][m][n][c] * r, uu = acc[ai][1][m][n][c] * r; v[4 * n + c] = g * sigm(g) * uu; }
;         u32x4 w; w.x = pk2(v[0], v[1]); w.y = pk2(v[2], v[3]); w.z = pk2(v[4], v[5]); w.w = pk2(v[6], v[7]);
;         *(u32x4*)(hbuf + (unsigned)(row0 + ai * 128 + m * 16) * DFF + col0) = w;
;       }
	v_pk_mul_f32 v[116:117], v[118:119], v[126:127]
	v_cvt_pk_bf16_f32 v118, v112, v113
	v_pk_mul_f32 v[114:115], v[114:115], v[116:117]
	v_cvt_pk_bf16_f32 v116, v120, v121
	v_cvt_pk_bf16_f32 v119, v114, v115
	v_mul_lo_u32 v114, v190, s63
	v_mov_b32_e32 v115, v137
	v_lshl_add_u64 v[120:121], v[114:115], 1, s[38:39]
	v_lshlrev_b64 v[112:113], 1, v[182:183]
	v_pk_mul_f32 v[108:109], v[108:109], v[176:177] op_sel_hi:[1,0]
	v_cvt_pk_bf16_f32 v117, v122, v123
	v_lshl_add_u64 v[120:121], v[120:121], 0, v[112:113]
	v_mul_f32_e32 v115, 0xbfb8aa3b, v108
	v_exp_f32_e32 v115, v115
	global_store_dwordx4 v[120:121], v[116:119], off
	v_pk_mul_f32 v[110:111], v[110:111], v[176:177] op_sel_hi:[1,0]
	v_pk_mul_f32 v[100:101], v[100:101], v[176:177] op_sel_hi:[1,0]
	v_mul_f32_e32 v116, 0xbfb8aa3b, v109
	v_exp_f32_e32 v117, v116
	v_add_f32_e32 v115, 1.0, v115
	v_rcp_f32_e32 v116, v115
	v_pk_mul_f32 v[104:105], v[104:105], v[176:177] op_sel_hi:[1,0]
	v_add_f32_e32 v115, 1.0, v117
	v_mul_f32_e32 v117, 0xbfb8aa3b, v110
	v_exp_f32_e32 v118, v117
	v_mul_f32_e32 v117, 0xbfb8aa3b, v111
	v_exp_f32_e32 v119, v117
	v_rcp_f32_e32 v117, v115
	v_add_f32_e32 v115, 1.0, v118
	v_rcp_f32_e32 v118, v115
	v_add_f32_e32 v115, 1.0, v119
	v_rcp_f32_e32 v119, v115
	v_pk_mul_f32 v[108:109], v[108:109], v[116:117]
	v_pk_mul_f32 v[102:103], v[102:103], v[176:177] op_sel_hi:[1,0]
	v_pk_mul_f32 v[100:101], v[100:101], v[108:109]
	v_pk_mul_f32 v[108:109], v[110:111], v[118:119]
	v_mul_f32_e32 v110, 0xbfb8aa3b, v104
	v_exp_f32_e32 v110, v110
	v_pk_mul_f32 v[102:103], v[102:103], v[108:109]
	v_mul_f32_e32 v108, 0xbfb8aa3b, v105
	v_pk_mul_f32 v[106:107], v[106:107], v[176:177] op_sel_hi:[1,0]
	v_exp_f32_e32 v109, v108
	v_add_f32_e32 v108, 1.0, v110
	v_mul_f32_e32 v110, 0xbfb8aa3b, v106
	v_mul_f32_e32 v111, 0xbfb8aa3b, v107
	v_exp_f32_e32 v110, v110
	v_exp_f32_e32 v111, v111
	v_add_f32_e32 v109, 1.0, v109
	v_rcp_f32_e32 v108, v108
	v_rcp_f32_e32 v109, v109
	v_add_f32_e32 v110, 1.0, v110
	v_add_f32_e32 v111, 1.0, v111
	v_rcp_f32_e32 v110, v110
	v_rcp_f32_e32 v111, v111
	v_pk_mul_f32 v[96:97], v[96:97], v[176:177] op_sel_hi:[1,0]
	v_pk_mul_f32 v[104:105], v[104:105], v[108:109]
	v_pk_mul_f32 v[92:93], v[92:93], v[152:153] op_sel_hi:[1,0]
	v_pk_mul_f32 v[104:105], v[96:97], v[104:105]
	v_pk_mul_f32 v[96:97], v[98:99], v[176:177] op_sel_hi:[1,0]
	v_pk_mul_f32 v[98:99], v[106:107], v[110:111]
	v_pk_mul_f32 v[94:95], v[94:95], v[152:153] op_sel_hi:[1,0]
	v_pk_mul_f32 v[106:107], v[96:97], v[98:99]
	v_cvt_pk_bf16_f32 v96, v100, v101
	v_add_u32_e32 v100, 0xb000, v114
	v_mov_b32_e32 v101, v137
	v_lshl_add_u64 v[100:101], v[100:101], 1, s[38:39]
	v_cvt_pk_bf16_f32 v97, v102, v103
	v_cvt_pk_bf16_f32 v98, v104, v105
	v_cvt_pk_bf16_f32 v99, v106, v107
	v_lshl_add_u64 v[100:101], v[100:101], 0, v[112:113]
	v_mul_f32_e32 v102, 0xbfb8aa3b, v92
	global_store_dwordx4 v[100:101], v[96:99], off
	v_exp_f32_e32 v102, v102
	v_pk_mul_f32 v[84:85], v[84:85], v[152:153] op_sel_hi:[1,0]
	v_mul_f32_e32 v96, 0xbfb8aa3b, v93
	v_exp_f32_e32 v97, v96
	v_mul_f32_e32 v98, 0xbfb8aa3b, v94
	v_mul_f32_e32 v99, 0xbfb8aa3b, v95
	v_exp_f32_e32 v98, v98
	v_exp_f32_e32 v99, v99
	v_add_f32_e32 v96, 1.0, v102
	v_add_f32_e32 v97, 1.0, v97
	v_rcp_f32_e32 v96, v96
	v_rcp_f32_e32 v97, v97
	v_add_f32_e32 v98, 1.0, v98
	v_add_f32_e32 v99, 1.0, v99
	v_rcp_f32_e32 v98, v98
	v_rcp_f32_e32 v99, v99
	v_pk_mul_f32 v[92:93], v[92:93], v[96:97]
	v_pk_mul_f32 v[88:89], v[88:89], v[152:153] op_sel_hi:[1,0]
	v_pk_mul_f32 v[84:85], v[84:85], v[92:93]
	v_pk_mul_f32 v[92:93], v[94:95], v[98:99]
	v_mul_f32_e32 v94, 0xbfb8aa3b, v88
	v_exp_f32_e32 v94, v94
	v_pk_mul_f32 v[86:87], v[86:87], v[152:153] op_sel_hi:[1,0]
	v_pk_mul_f32 v[90:91], v[90:91], v[152:153] op_sel_hi:[1,0]
	v_pk_mul_f32 v[86:87], v[86:87], v[92:93]
	v_mul_f32_e32 v92, 0xbfb8aa3b, v89
	v_exp_f32_e32 v93, v92
	v_add_f32_e32 v92, 1.0, v94
	v_mul_f32_e32 v94, 0xbfb8aa3b, v90
	v_mul_f32_e32 v95, 0xbfb8aa3b, v91
	v_exp_f32_e32 v94, v94
	v_exp_f32_e32 v95, v95
	v_add_f32_e32 v93, 1.0, v93
	v_rcp_f32_e32 v92, v92
	v_rcp_f32_e32 v93, v93
	v_add_f32_e32 v94, 1.0, v94
	v_add_f32_e32 v95, 1.0, v95
	v_rcp_f32_e32 v94, v94
	v_rcp_f32_e32 v95, v95
	v_pk_mul_f32 v[80:81], v[80:81], v[152:153] op_sel_hi:[1,0]
	v_pk_mul_f32 v[88:89], v[88:89], v[92:93]
	v_pk_mul_f32 v[76:77], v[76:77], v[150:151] op_sel_hi:[1,0]
	v_pk_mul_f32 v[88:89], v[80:81], v[88:89]
	v_pk_mul_f32 v[80:81], v[82:83], v[152:153] op_sel_hi:[1,0]
	v_pk_mul_f32 v[82:83], v[90:91], v[94:95]
	v_pk_mul_f32 v[78:79], v[78:79], v[150:151] op_sel_hi:[1,0]
	v_pk_mul_f32 v[90:91], v[80:81], v[82:83]
	v_cvt_pk_bf16_f32 v80, v84, v85
	v_add_u32_e32 v84, 0x16000, v114
	v_mov_b32_e32 v85, v137
	v_lshl_add_u64 v[84:85], v[84:85], 1, s[38:39]
	v_cvt_pk_bf16_f32 v81, v86, v87
	v_cvt_pk_bf16_f32 v82, v88, v89
	v_cvt_pk_bf16_f32 v83, v90, v91
	v_lshl_add_u64 v[84:85], v[84:85], 0, v[112:113]
	v_mul_f32_e32 v86, 0xbfb8aa3b, v76
	global_store_dwordx4 v[84:85], v[80:83], off
	v_exp_f32_e32 v86, v86
	v_pk_mul_f32 v[68:69], v[68:69], v[150:151] op_sel_hi:[1,0]
	v_mul_f32_e32 v80, 0xbfb8aa3b, v77
	v_exp_f32_e32 v81, v80
	v_mul_f32_e32 v82, 0xbfb8aa3b, v78
	v_mul_f32_e32 v83, 0xbfb8aa3b, v79
	v_exp_f32_e32 v82, v82
	v_exp_f32_e32 v83, v83
	v_add_f32_e32 v80, 1.0, v86
	v_add_f32_e32 v81, 1.0, v81
	v_rcp_f32_e32 v80, v80
	v_rcp_f32_e32 v81, v81
	v_add_f32_e32 v82, 1.0, v82
	v_add_f32_e32 v83, 1.0, v83
	v_rcp_f32_e32 v82, v82
	v_rcp_f32_e32 v83, v83
	v_pk_mul_f32 v[76:77], v[76:77], v[80:81]
	v_pk_mul_f32 v[72:73], v[72:73], v[150:151] op_sel_hi:[1,0]
	v_pk_mul_f32 v[68:69], v[68:69], v[76:77]
	v_pk_mul_f32 v[76:77], v[78:79], v[82:83]
	v_mul_f32_e32 v78, 0xbfb8aa3b, v72
	v_exp_f32_e32 v78, v78
	v_pk_mul_f32 v[70:71], v[70:71], v[150:151] op_sel_hi:[1,0]
	v_pk_mul_f32 v[74:75], v[74:75], v[150:151] op_sel_hi:[1,0]
	v_pk_mul_f32 v[70:71], v[70:71], v[76:77]
	v_mul_f32_e32 v76, 0xbfb8aa3b, v73
	v_exp_f32_e32 v77, v76
	v_add_f32_e32 v76, 1.0, v78
	v_mul_f32_e32 v78, 0xbfb8aa3b, v74
	v_mul_f32_e32 v79, 0xbfb8aa3b, v75
	v_exp_f32_e32 v78, v78
	v_exp_f32_e32 v79, v79
	v_add_f32_e32 v77, 1.0, v77
	v_rcp_f32_e32 v76, v76
	v_rcp_f32_e32 v77, v77
	v_add_f32_e32 v78, 1.0, v78
	v_add_f32_e32 v79, 1.0, v79
	v_rcp_f32_e32 v78, v78
	v_rcp_f32_e32 v79, v79
	v_pk_mul_f32 v[64:65], v[64:65], v[150:151] op_sel_hi:[1,0]
	v_pk_mul_f32 v[72:73], v[72:73], v[76:77]
	s_nop 0
	v_pk_mul_f32 v[72:73], v[64:65], v[72:73]
	v_pk_mul_f32 v[64:65], v[66:67], v[150:151] op_sel_hi:[1,0]
	v_pk_mul_f32 v[66:67], v[74:75], v[78:79]
	s_nop 0
	v_pk_mul_f32 v[74:75], v[64:65], v[66:67]
	v_cvt_pk_bf16_f32 v64, v68, v69
	v_add_u32_e32 v68, 0x21000, v114
	v_mov_b32_e32 v69, v137
	v_lshl_add_u64 v[68:69], v[68:69], 1, s[38:39]
	v_cvt_pk_bf16_f32 v65, v70, v71
	v_cvt_pk_bf16_f32 v66, v72, v73
	v_cvt_pk_bf16_f32 v67, v74, v75
	v_lshl_add_u64 v[68:69], v[68:69], 0, v[112:113]
	global_store_dwordx4 v[68:69], v[64:67], off
	s_cmp_lg_u32 s99, 0
	s_cbranch_scc1 .Lsplit_gu2b_tail
; __device__ __forceinline__ unsigned pk2(float lo, float hi) { f32x2_t v = {lo, hi}; bf16x2_t b = __builtin_convertvector(v, bf16x2_t); return __builtin_bit_cast(unsigned, b); }
; __device__ __forceinline__ float sigm(float x) { return frcp(1.f + fexp2(-LOG2E * x)); }
;   __device__ __forceinline__ void operator()(const pg8::f32x4 (&acc)[2][2][4][2], const pg8::Unit& u, int wr, int wc, int fr, int fq) const {
;     ...
;     for (int ai = 0; ai < 2; ++ai) {
;       float rs[4];
; #pragma unroll
;       for (int m = 0; m < 4; ++m) { const f32x4 a = *(const f32x4*)(ssq + (unsigned)(row0 + ai * 128 + m * 16) * 16 + 4 * fq); rs[m] = (a[0] + a[1]) + (a[2] + a[3]); }
; #pragma unroll
;       for (int m = 0; m < 4; ++m) { float v = rs[m]; v += __shfl_xor(v, 16); v += __shfl_xor(v, 32); rs[m] = rsqrtf(v * (1.f / 1024.f) + EPS); }
; #pragma unroll
;       for (int m = 0; m < 4; ++m) {
;         const float r = rs[m]; float v[8];
; #pragma unroll
;         for (int n = 0; n < 2; ++n)
; #pragma unroll
;           for (int c = 0; c < 4; ++c) { const float g = acc[ai][0][m][n][c] * r, uu = acc[ai][1][m][n][c] * r; v[4 * n + c] = g * sigm(g) * uu; }
;         u32x4 w; w.x = pk2(v[0], v[1]); w.y = pk2(v[2], v[3]); w.z = pk2(v[4], v[5]); w.w = pk2(v[6], v[7]);
;         *(u32x4*)(hbuf + (unsigned)(row0 + ai * 128 + m * 16) * DFF + col0) = w;
	v_add_u32_e32 v68, 0x900, v136
	v_mov_b32_e32 v69, v137
	v_add_u32_e32 v64, 0x800, v136
	v_mov_b32_e32 v65, v137
	v_lshl_add_u64 v[64:65], v[64:65], 2, v[138:139]
	v_lshl_add_u64 v[68:69], v[68:69], 2, v[138:139]
	global_load_dwordx4 v[64:67], v[64:65], off
	v_add_u32_e32 v72, 0xa00, v136
	global_load_dwordx4 v[68:71], v[68:69], off
	v_mov_b32_e32 v73, v137
	v_add_u32_e32 v136, 0xb00, v136
	v_lshl_add_u64 v[72:73], v[72:73], 2, v[138:139]
	v_lshl_add_u64 v[76:77], v[136:137], 2, v[138:139]
	global_load_dwordx4 v[72:75], v[72:73], off
	v_add_u32_e32 v136, 0x58000, v114
	global_load_dwordx4 v[76:79], v[76:77], off
	s_waitcnt vmcnt(3)
	v_mov_b32_e32 v80, v65
	v_mov_b32_e32 v81, v66
	v_mov_b32_e32 v65, v67
	s_waitcnt vmcnt(2)
	v_mov_b32_e32 v66, v69
	v_mov_b32_e32 v67, v70
	v_mov_b32_e32 v69, v71
	v_pk_add_f32 v[64:65], v[80:81], v[64:65]
	v_pk_add_f32 v[66:67], v[66:67], v[68:69]
	v_mov_b32_e32 v69, v64
	v_mov_b32_e32 v68, v66
	v_mov_b32_e32 v64, v67
	v_pk_add_f32 v[64:65], v[68:69], v[64:65]
	ds_bpermute_b32 v67, v172, v65
	ds_bpermute_b32 v66, v172, v64
	s_waitcnt vmcnt(1)
	v_mov_b32_e32 v68, v73
	v_mov_b32_e32 v69, v74
	v_mov_b32_e32 v73, v75
	s_waitcnt vmcnt(0)
	v_mov_b32_e32 v70, v77
	s_waitcnt lgkmcnt(0)
	v_pk_add_f32 v[64:65], v[64:65], v[66:67]
	ds_bpermute_b32 v67, v173, v65
	ds_bpermute_b32 v66, v173, v64
	v_mov_b32_e32 v71, v78
	v_mov_b32_e32 v77, v79
	v_pk_add_f32 v[68:69], v[68:69], v[72:73]
	v_pk_add_f32 v[70:71], v[70:71], v[76:77]
	s_waitcnt lgkmcnt(0)
	v_pk_add_f32 v[64:65], v[64:65], v[66:67]
	v_mov_b32_e32 v67, v68
	v_pk_fma_f32 v[64:65], v[64:65], s[18:19], v[148:149] op_sel_hi:[1,0,0]
	v_mov_b32_e32 v68, v71
	v_mul_f32_e32 v66, 0x4b800000, v65
	v_cmp_gt_f32_e32 vcc, s62, v65
	v_cmp_gt_f32_e64 s[6:7], s62, v64
	s_nop 0
	v_cndmask_b32_e32 v65, v65, v66, vcc
	v_mov_b32_e32 v66, v70
	v_pk_add_f32 v[66:67], v[66:67], v[68:69]
	ds_bpermute_b32 v69, v172, v67
	ds_bpermute_b32 v68, v172, v66
	v_rsq_f32_e32 v72, v65
	v_mul_f32_e32 v65, 0x4b800000, v64
	v_cndmask_b32_e64 v64, v64, v65, s[6:7]
	v_rsq_f32_e32 v70, v64
	s_waitcnt lgkmcnt(0)
	v_pk_add_f32 v[64:65], v[66:67], v[68:69]
	ds_bpermute_b32 v67, v173, v65
	ds_bpermute_b32 v66, v173, v64
	v_mul_f32_e32 v68, 0x45800000, v72
	v_cndmask_b32_e32 v68, v72, v68, vcc
	v_mul_f32_e32 v69, 0x45800000, v70
	v_pk_mul_f32 v[62:63], v[62:63], v[68:69] op_sel_hi:[1,0]
	s_waitcnt lgkmcnt(0)
	v_pk_add_f32 v[64:65], v[64:65], v[66:67]
	v_pk_mul_f32 v[56:57], v[56:57], v[68:69] op_sel_hi:[1,0]
	v_pk_fma_f32 v[64:65], v[64:65], s[18:19], v[148:149] op_sel_hi:[1,0,0]
	v_pk_mul_f32 v[54:55], v[54:55], v[68:69] op_sel_hi:[1,0]
	v_mul_f32_e32 v66, 0x4b800000, v65
	v_cmp_gt_f32_e32 vcc, s62, v65
	v_cmp_gt_f32_e64 s[8:9], s62, v64
	v_pk_mul_f32 v[58:59], v[58:59], v[68:69] op_sel_hi:[1,0]
	v_cndmask_b32_e32 v65, v65, v66, vcc
	v_mul_f32_e32 v66, 0x4b800000, v64
	v_rsq_f32_e32 v65, v65
	v_cndmask_b32_e64 v64, v64, v66, s[8:9]
	v_rsq_f32_e32 v67, v64
	v_cndmask_b32_e64 v66, v70, v69, s[6:7]
	v_mul_f32_e32 v64, 0x45800000, v65
	v_pk_mul_f32 v[70:71], v[60:61], v[68:69] op_sel_hi:[1,0]
	v_cndmask_b32_e32 v64, v65, v64, vcc
	v_mul_f32_e32 v65, 0x45800000, v67
	v_mul_f32_e32 v60, 0xbfb8aa3b, v70
	v_exp_f32_e32 v61, v60
	v_cndmask_b32_e64 v60, v67, v65, s[8:9]
	v_mul_f32_e32 v65, 0xbfb8aa3b, v71
	v_exp_f32_e32 v65, v65
	v_add_f32_e32 v61, 1.0, v61
	v_rcp_f32_e32 v72, v61
	v_mul_f32_e32 v67, 0xbfb8aa3b, v63
	v_add_f32_e32 v61, 1.0, v65
	v_mul_f32_e32 v65, 0xbfb8aa3b, v62
	v_exp_f32_e32 v65, v65
	v_exp_f32_e32 v67, v67
	v_rcp_f32_e32 v73, v61
	v_pk_mul_f32 v[52:53], v[52:53], v[68:69] op_sel_hi:[1,0]
	v_add_f32_e32 v61, 1.0, v65
	v_rcp_f32_e32 v74, v61
	v_add_f32_e32 v61, 1.0, v67
	v_rcp_f32_e32 v75, v61
	v_mul_f32_e32 v61, 0xbfb8aa3b, v56
	v_exp_f32_e32 v61, v61
	v_pk_mul_f32 v[70:71], v[70:71], v[72:73]
	v_pk_mul_f32 v[62:63], v[62:63], v[74:75]
	v_pk_mul_f32 v[52:53], v[52:53], v[70:71]
	v_pk_mul_f32 v[54:55], v[54:55], v[62:63]
	v_mul_f32_e32 v62, 0xbfb8aa3b, v57
	v_exp_f32_e32 v63, v62
	v_add_f32_e32 v61, 1.0, v61
	v_rcp_f32_e32 v62, v61
	v_pk_mul_f32 v[48:49], v[48:49], v[68:69] op_sel_hi:[1,0]
	v_add_f32_e32 v61, 1.0, v63
	v_mul_f32_e32 v63, 0xbfb8aa3b, v58
	v_exp_f32_e32 v65, v63
	v_mul_f32_e32 v63, 0xbfb8aa3b, v59
	v_exp_f32_e32 v67, v63
	v_rcp_f32_e32 v63, v61
	v_add_f32_e32 v61, 1.0, v65
	v_rcp_f32_e32 v70, v61
	v_add_f32_e32 v61, 1.0, v67
	v_rcp_f32_e32 v71, v61
	v_pk_mul_f32 v[56:57], v[56:57], v[62:63]
	v_pk_mul_f32 v[44:45], v[44:45], v[66:67] op_sel_hi:[1,0]
	v_pk_mul_f32 v[56:57], v[48:49], v[56:57]
	v_pk_mul_f32 v[48:49], v[50:51], v[68:69] op_sel_hi:[1,0]
	v_pk_mul_f32 v[50:51], v[58:59], v[70:71]
	v_pk_mul_f32 v[46:47], v[46:47], v[66:67] op_sel_hi:[1,0]
	v_pk_mul_f32 v[58:59], v[48:49], v[50:51]
	v_cvt_pk_bf16_f32 v48, v52, v53
	v_lshl_add_u64 v[52:53], v[136:137], 1, s[38:39]
	v_cvt_pk_bf16_f32 v49, v54, v55
	v_cvt_pk_bf16_f32 v50, v56, v57
	v_cvt_pk_bf16_f32 v51, v58, v59
	v_lshl_add_u64 v[52:53], v[52:53], 0, v[112:113]
	v_mul_f32_e32 v54, 0xbfb8aa3b, v44
	global_store_dwordx4 v[52:53], v[48:51], off
	v_exp_f32_e32 v54, v54
	v_pk_mul_f32 v[36:37], v[36:37], v[66:67] op_sel_hi:[1,0]
	v_mul_f32_e32 v48, 0xbfb8aa3b, v45
	v_exp_f32_e32 v49, v48
	v_mul_f32_e32 v50, 0xbfb8aa3b, v46
	v_mul_f32_e32 v51, 0xbfb8aa3b, v47
	v_exp_f32_e32 v50, v50
	v_exp_f32_e32 v51, v51
	v_add_f32_e32 v48, 1.0, v54
	v_add_f32_e32 v49, 1.0, v49
	v_rcp_f32_e32 v48, v48
	v_rcp_f32_e32 v49, v49
	v_add_f32_e32 v50, 1.0, v50
	v_add_f32_e32 v51, 1.0, v51
	v_rcp_f32_e32 v50, v50
	v_rcp_f32_e32 v51, v51
	v_pk_mul_f32 v[44:45], v[44:45], v[48:49]
	v_pk_mul_f32 v[40:41], v[40:41], v[66:67] op_sel_hi:[1,0]
; __device__ __forceinline__ unsigned pk2(float lo, float hi) { f32x2_t v = {lo, hi}; bf16x2_t b = __builtin_convertvector(v, bf16x2_t); return __builtin_bit_cast(unsigned, b); }
; __device__ __forceinline__ float sigm(float x) { return frcp(1.f + fexp2(-LOG2E * x)); }
; #define PG8_BAR __builtin_amdgcn_s_barrier()
; template <class Epi, class Sched, bool ALIGN_EPI = false, bool SP2 = false, bool F16 = false, bool TOKPERM = false>
; __device__ __forceinline__ void gemm_phase(PG8_LAS unsigned char* lds, const Gemm g, const Sched& S, const Epi& E, int wv) {
;     ...
;         if constexpr (ALIGN_EPI) { if (wr == 0) PG8_BAR; }
;         if constexpr (!Epi::AFTER_DRAIN) { E(acc, cur, wr, wc, fr, fq); S.done(cur); }
;         if (!has_next) break;
; #pragma unroll
;         for (int a = 0; a < 2; ++a)
; #pragma unroll
;             for (int b = 0; b < 2; ++b)
; #pragma unroll
;                 for (int m = 0; m < 4; ++m)
; #pragma unroll
;                     for (int n = 0; n < 2; ++n) acc[a][b][m][n] = (f32x4){0.f, 0.f, 0.f, 0.f};
;         cur = nxt; cA = nA; cB = nB; ++ui;
;         if constexpr (ALIGN_EPI) { if (wr == 1) PG8_BAR; }
;   __device__ __forceinline__ void operator()(const pg8::f32x4 (&acc)[2][2][4][2], const pg8::Unit& u, int wr, int wc, int fr, int fq) const {
;     ...
;       for (int m = 0; m < 4; ++m) {
;         const float r = rs[m]; float v[8];
; #pragma unroll
;         for (int n = 0; n < 2; ++n)
; #pragma unroll
;           for (int c = 0; c < 4; ++c) { const float g = acc[ai][0][m][n][c] * r, uu = acc[ai][1][m][n][c] * r; v[4 * n + c] = g * sigm(g) * uu; }
;         u32x4 w; w.x = pk2(v[0], v[1]); w.y = pk2(v[2], v[3]); w.z = pk2(v[4], v[5]); w.w = pk2(v[6], v[7]);
;         *(u32x4*)(hbuf + (unsigned)(row0 + ai * 128 + m * 16) * DFF + col0) = w;
;       }
	v_pk_mul_f32 v[36:37], v[36:37], v[44:45]
	v_pk_mul_f32 v[44:45], v[46:47], v[50:51]
	v_mul_f32_e32 v46, 0xbfb8aa3b, v40
	v_exp_f32_e32 v46, v46
	v_pk_mul_f32 v[38:39], v[38:39], v[66:67] op_sel_hi:[1,0]
	v_pk_mul_f32 v[42:43], v[42:43], v[66:67] op_sel_hi:[1,0]
	v_pk_mul_f32 v[38:39], v[38:39], v[44:45]
	v_mul_f32_e32 v44, 0xbfb8aa3b, v41
	v_exp_f32_e32 v45, v44
	v_add_f32_e32 v44, 1.0, v46
	v_mul_f32_e32 v46, 0xbfb8aa3b, v42
	v_mul_f32_e32 v47, 0xbfb8aa3b, v43
	v_exp_f32_e32 v46, v46
	v_exp_f32_e32 v47, v47
	v_add_f32_e32 v45, 1.0, v45
	v_rcp_f32_e32 v44, v44
	v_rcp_f32_e32 v45, v45
	v_add_f32_e32 v46, 1.0, v46
	v_add_f32_e32 v47, 1.0, v47
	v_rcp_f32_e32 v46, v46
	v_rcp_f32_e32 v47, v47
	v_pk_mul_f32 v[32:33], v[32:33], v[66:67] op_sel_hi:[1,0]
	v_pk_mul_f32 v[40:41], v[40:41], v[44:45]
	v_add_u32_e32 v136, 0x63000, v114
	v_pk_mul_f32 v[40:41], v[32:33], v[40:41]
	v_pk_mul_f32 v[32:33], v[34:35], v[66:67] op_sel_hi:[1,0]
	v_pk_mul_f32 v[34:35], v[42:43], v[46:47]
	v_pk_mul_f32 v[28:29], v[28:29], v[64:65] op_sel_hi:[1,0]
	v_pk_mul_f32 v[42:43], v[32:33], v[34:35]
	v_cvt_pk_bf16_f32 v32, v36, v37
	v_lshl_add_u64 v[36:37], v[136:137], 1, s[38:39]
	v_cvt_pk_bf16_f32 v33, v38, v39
	v_cvt_pk_bf16_f32 v34, v40, v41
	v_cvt_pk_bf16_f32 v35, v42, v43
	v_lshl_add_u64 v[36:37], v[36:37], 0, v[112:113]
	v_mul_f32_e32 v38, 0xbfb8aa3b, v28
	global_store_dwordx4 v[36:37], v[32:35], off
	v_pk_mul_f32 v[30:31], v[30:31], v[64:65] op_sel_hi:[1,0]
	v_exp_f32_e32 v38, v38
	v_mul_f32_e32 v32, 0xbfb8aa3b, v29
	v_exp_f32_e32 v33, v32
	v_mul_f32_e32 v34, 0xbfb8aa3b, v30
	v_mul_f32_e32 v35, 0xbfb8aa3b, v31
	v_exp_f32_e32 v34, v34
	v_exp_f32_e32 v35, v35
	v_add_f32_e32 v32, 1.0, v38
	v_add_f32_e32 v33, 1.0, v33
	v_rcp_f32_e32 v32, v32
	v_rcp_f32_e32 v33, v33
	v_add_f32_e32 v34, 1.0, v34
	v_add_f32_e32 v35, 1.0, v35
	v_rcp_f32_e32 v34, v34
	v_rcp_f32_e32 v35, v35
	v_pk_mul_f32 v[20:21], v[20:21], v[64:65] op_sel_hi:[1,0]
	v_pk_mul_f32 v[28:29], v[28:29], v[32:33]
	v_pk_mul_f32 v[24:25], v[24:25], v[64:65] op_sel_hi:[1,0]
	v_pk_mul_f32 v[20:21], v[20:21], v[28:29]
	v_pk_mul_f32 v[28:29], v[30:31], v[34:35]
	v_mul_f32_e32 v30, 0xbfb8aa3b, v24
	v_exp_f32_e32 v30, v30
	v_pk_mul_f32 v[22:23], v[22:23], v[64:65] op_sel_hi:[1,0]
	v_pk_mul_f32 v[26:27], v[26:27], v[64:65] op_sel_hi:[1,0]
	v_pk_mul_f32 v[22:23], v[22:23], v[28:29]
	v_mul_f32_e32 v28, 0xbfb8aa3b, v25
	v_exp_f32_e32 v29, v28
	v_add_f32_e32 v28, 1.0, v30
	v_mul_f32_e32 v30, 0xbfb8aa3b, v26
	v_mul_f32_e32 v31, 0xbfb8aa3b, v27
	v_exp_f32_e32 v30, v30
	v_exp_f32_e32 v31, v31
	v_add_f32_e32 v29, 1.0, v29
	v_rcp_f32_e32 v28, v28
	v_rcp_f32_e32 v29, v29
	v_add_f32_e32 v30, 1.0, v30
	v_add_f32_e32 v31, 1.0, v31
	v_rcp_f32_e32 v30, v30
	v_rcp_f32_e32 v31, v31
	v_pk_mul_f32 v[16:17], v[16:17], v[64:65] op_sel_hi:[1,0]
	v_pk_mul_f32 v[24:25], v[24:25], v[28:29]
	v_add_u32_e32 v136, 0x6e000, v114
	v_pk_mul_f32 v[24:25], v[16:17], v[24:25]
	v_pk_mul_f32 v[16:17], v[18:19], v[64:65] op_sel_hi:[1,0]
	v_pk_mul_f32 v[18:19], v[26:27], v[30:31]
	v_pk_mul_f32 v[12:13], v[12:13], v[60:61] op_sel_hi:[1,0]
	v_pk_mul_f32 v[26:27], v[16:17], v[18:19]
	v_cvt_pk_bf16_f32 v16, v20, v21
	v_lshl_add_u64 v[20:21], v[136:137], 1, s[38:39]
	v_cvt_pk_bf16_f32 v17, v22, v23
	v_cvt_pk_bf16_f32 v18, v24, v25
	v_cvt_pk_bf16_f32 v19, v26, v27
	v_lshl_add_u64 v[20:21], v[20:21], 0, v[112:113]
	v_mul_f32_e32 v22, 0xbfb8aa3b, v12
	global_store_dwordx4 v[20:21], v[16:19], off
	v_pk_mul_f32 v[14:15], v[14:15], v[60:61] op_sel_hi:[1,0]
	v_exp_f32_e32 v22, v22
	v_mul_f32_e32 v16, 0xbfb8aa3b, v13
	v_exp_f32_e32 v17, v16
	v_mul_f32_e32 v18, 0xbfb8aa3b, v14
	v_mul_f32_e32 v19, 0xbfb8aa3b, v15
	v_exp_f32_e32 v18, v18
	v_exp_f32_e32 v19, v19
	v_add_f32_e32 v16, 1.0, v22
	v_add_f32_e32 v17, 1.0, v17
	v_rcp_f32_e32 v16, v16
	v_rcp_f32_e32 v17, v17
	v_add_f32_e32 v18, 1.0, v18
	v_add_f32_e32 v19, 1.0, v19
	v_rcp_f32_e32 v18, v18
	v_rcp_f32_e32 v19, v19
	v_pk_mul_f32 v[4:5], v[4:5], v[60:61] op_sel_hi:[1,0]
	v_pk_mul_f32 v[12:13], v[12:13], v[16:17]
	v_pk_mul_f32 v[8:9], v[8:9], v[60:61] op_sel_hi:[1,0]
	v_pk_mul_f32 v[4:5], v[4:5], v[12:13]
	v_pk_mul_f32 v[12:13], v[14:15], v[18:19]
	v_mul_f32_e32 v14, 0xbfb8aa3b, v8
	v_exp_f32_e32 v14, v14
	v_pk_mul_f32 v[6:7], v[6:7], v[60:61] op_sel_hi:[1,0]
	v_pk_mul_f32 v[10:11], v[10:11], v[60:61] op_sel_hi:[1,0]
	v_pk_mul_f32 v[6:7], v[6:7], v[12:13]
	v_mul_f32_e32 v12, 0xbfb8aa3b, v9
	v_exp_f32_e32 v13, v12
	v_add_f32_e32 v12, 1.0, v14
	v_mul_f32_e32 v14, 0xbfb8aa3b, v10
	v_mul_f32_e32 v15, 0xbfb8aa3b, v11
	v_exp_f32_e32 v14, v14
	v_exp_f32_e32 v15, v15
	v_add_f32_e32 v13, 1.0, v13
	v_rcp_f32_e32 v12, v12
	v_rcp_f32_e32 v13, v13
	v_add_f32_e32 v14, 1.0, v14
	v_add_f32_e32 v15, 1.0, v15
	v_rcp_f32_e32 v14, v14
	v_rcp_f32_e32 v15, v15
	v_pk_mul_f32 v[0:1], v[0:1], v[60:61] op_sel_hi:[1,0]
	v_pk_mul_f32 v[8:9], v[8:9], v[12:13]
	v_add_u32_e32 v136, 0x79000, v114
	v_pk_mul_f32 v[8:9], v[0:1], v[8:9]
	v_pk_mul_f32 v[0:1], v[2:3], v[60:61] op_sel_hi:[1,0]
	v_pk_mul_f32 v[2:3], v[10:11], v[14:15]
	s_andn2_b64 vcc, exec, s[4:5]
	v_pk_mul_f32 v[10:11], v[0:1], v[2:3]
	v_cvt_pk_bf16_f32 v0, v4, v5
	v_lshl_add_u64 v[4:5], v[136:137], 1, s[38:39]
	v_cvt_pk_bf16_f32 v1, v6, v7
	v_cvt_pk_bf16_f32 v2, v8, v9
	v_cvt_pk_bf16_f32 v3, v10, v11
	v_lshl_add_u64 v[4:5], v[4:5], 0, v[112:113]
	global_store_dwordx4 v[4:5], v[0:3], off
	s_mov_b64 s[4:5], -1
	s_cbranch_vccnz .LBB0_1603
.Lsplit_gu2b_cont:
	s_andn2_b64 vcc, exec, s[12:13]
	s_cbranch_vccnz .LBB0_1602
	s_barrier
	s_branch .LBB0_1602
.Lsplit_gu2b_tail:
	s_andn2_b64 vcc, exec, s[4:5]
	s_mov_b64 s[4:5], -1
	s_cbranch_vccnz .LBB0_1603
	s_branch .Lsplit_gu2b_cont
